# GEMM k-loop: both halves LDS fragment reads issued up front (2nd half into spare VGPRs), DMA between, 32 MFMA back-to-back
# speedup vs baseline: 1.0062x; 1.0041x over previous
.LBB0_226:
	s_and_b32 s0, s19, 0x2000
	s_xor_b32 s1, s0, 0x2000
	s_lshl_b32 s0, s0, 1
	v_add_u32_e32 v0, s0, v151
	v_add_u32_e32 v159, s0, v152
	v_add_u32_e32 v126, v0, v157
	v_add_u32_e32 v164, v159, v157
	ds_read_b128 v[82:85], v126
	ds_read_b128 v[86:89], v126 offset:2048
	ds_read_b128 v[122:125], v126 offset:4096
	ds_read_b128 v[126:129], v126 offset:6144
	ds_read_b128 v[130:133], v164 offset:32768
	ds_read_b128 v[134:137], v164 offset:34816
	ds_read_b128 v[160:163], v164 offset:36864
	ds_read_b128 v[164:167], v164 offset:38912
	v_lshl_add_u32 v250, s1, 1, v95
	v_lshl_add_u32 v255, v147, 1, v250
	v_add_u32_e32 v180, 0x8000, v255
	v_readfirstlane_b32 s1, v255
	v_lshl_add_u64 v[246:247], v[66:67], 0, s[44:45]
	s_mov_b32 m0, s1
	v_readfirstlane_b32 s1, v180
	v_lshl_add_u32 v255, v148, 1, v250
	v_lshl_add_u64 v[248:249], v[74:75], 0, s[44:45]
	global_load_lds_dwordx4 v[246:247], off
	s_mov_b32 m0, s1
	v_add_u32_e32 v180, 0x8000, v255
	v_readfirstlane_b32 s1, v255
	global_load_lds_dwordx4 v[248:249], off
	v_lshl_add_u64 v[246:247], v[68:69], 0, s[44:45]
	s_mov_b32 m0, s1
	v_readfirstlane_b32 s1, v180
	v_lshl_add_u32 v255, v149, 1, v250
	v_lshl_add_u64 v[248:249], v[76:77], 0, s[44:45]
	global_load_lds_dwordx4 v[246:247], off
	s_mov_b32 m0, s1
	v_add_u32_e32 v180, 0x8000, v255
	v_readfirstlane_b32 s1, v255
	global_load_lds_dwordx4 v[248:249], off
	v_lshl_add_u64 v[246:247], v[70:71], 0, s[44:45]
	s_mov_b32 m0, s1
	v_readfirstlane_b32 s1, v180
	v_lshl_add_u32 v250, v150, 1, v250
	v_lshl_add_u64 v[248:249], v[78:79], 0, s[44:45]
	global_load_lds_dwordx4 v[246:247], off
	s_mov_b32 m0, s1
	v_add_u32_e32 v255, 0x8000, v250
	v_readfirstlane_b32 s1, v250
	global_load_lds_dwordx4 v[248:249], off
	v_lshl_add_u64 v[246:247], v[72:73], 0, s[44:45]
	s_mov_b32 m0, s1
	v_readfirstlane_b32 s1, v255
	v_lshl_add_u64 v[248:249], v[80:81], 0, s[44:45]
	global_load_lds_dwordx4 v[246:247], off
	s_mov_b32 m0, s1
	global_load_lds_dwordx4 v[248:249], off
	v_add_u32_e32 v0, v0, v158
	ds_read_b128 v[214:217], v0
	ds_read_b128 v[218:221], v0 offset:2048
	ds_read_b128 v[222:225], v0 offset:4096
	ds_read_b128 v[226:229], v0 offset:6144
	v_add_u32_e32 v0, v159, v158
	ds_read_b128 v[230:233], v0 offset:32768
	ds_read_b128 v[234:237], v0 offset:34816
	ds_read_b128 v[238:241], v0 offset:36864
	s_setprio 1
	s_waitcnt lgkmcnt(7)
	ds_read_b128 v[242:245], v0 offset:38912
	v_mfma_f32_16x16x32_bf16 v[2:5], v[130:133], v[82:85], v[2:5]
	v_mfma_f32_16x16x32_bf16 v[6:9], v[134:137], v[82:85], v[6:9]
	v_mfma_f32_16x16x32_bf16 v[10:13], v[160:163], v[82:85], v[10:13]
	v_mfma_f32_16x16x32_bf16 v[14:17], v[164:167], v[82:85], v[14:17]
	v_mfma_f32_16x16x32_bf16 v[18:21], v[130:133], v[86:89], v[18:21]
	v_mfma_f32_16x16x32_bf16 v[22:25], v[134:137], v[86:89], v[22:25]
	v_mfma_f32_16x16x32_bf16 v[26:29], v[160:163], v[86:89], v[26:29]
	v_mfma_f32_16x16x32_bf16 v[30:33], v[164:167], v[86:89], v[30:33]
	v_mfma_f32_16x16x32_bf16 v[34:37], v[130:133], v[122:125], v[34:37]
	v_mfma_f32_16x16x32_bf16 v[38:41], v[134:137], v[122:125], v[38:41]
	v_mfma_f32_16x16x32_bf16 v[42:45], v[160:163], v[122:125], v[42:45]
	v_mfma_f32_16x16x32_bf16 v[46:49], v[164:167], v[122:125], v[46:49]
	v_mfma_f32_16x16x32_bf16 v[50:53], v[130:133], v[126:129], v[50:53]
	v_mfma_f32_16x16x32_bf16 v[54:57], v[134:137], v[126:129], v[54:57]
	v_mfma_f32_16x16x32_bf16 v[58:61], v[160:163], v[126:129], v[58:61]
	v_mfma_f32_16x16x32_bf16 v[62:65], v[164:167], v[126:129], v[62:65]
	s_waitcnt lgkmcnt(0)
	v_mfma_f32_16x16x32_bf16 v[2:5], v[230:233], v[214:217], v[2:5]
	v_mfma_f32_16x16x32_bf16 v[6:9], v[234:237], v[214:217], v[6:9]
	v_mfma_f32_16x16x32_bf16 v[10:13], v[238:241], v[214:217], v[10:13]
	v_mfma_f32_16x16x32_bf16 v[14:17], v[242:245], v[214:217], v[14:17]
	v_mfma_f32_16x16x32_bf16 v[18:21], v[230:233], v[218:221], v[18:21]
	v_mfma_f32_16x16x32_bf16 v[22:25], v[234:237], v[218:221], v[22:25]
	v_mfma_f32_16x16x32_bf16 v[26:29], v[238:241], v[218:221], v[26:29]
	v_mfma_f32_16x16x32_bf16 v[30:33], v[242:245], v[218:221], v[30:33]
	v_mfma_f32_16x16x32_bf16 v[34:37], v[230:233], v[222:225], v[34:37]
	v_mfma_f32_16x16x32_bf16 v[38:41], v[234:237], v[222:225], v[38:41]
	v_mfma_f32_16x16x32_bf16 v[42:45], v[238:241], v[222:225], v[42:45]
	v_mfma_f32_16x16x32_bf16 v[46:49], v[242:245], v[222:225], v[46:49]
	v_mfma_f32_16x16x32_bf16 v[50:53], v[230:233], v[226:229], v[50:53]
	v_mfma_f32_16x16x32_bf16 v[54:57], v[234:237], v[226:229], v[54:57]
	v_mfma_f32_16x16x32_bf16 v[58:61], v[238:241], v[226:229], v[58:61]
	v_mfma_f32_16x16x32_bf16 v[62:65], v[242:245], v[226:229], v[62:65]
	s_setprio 0
	s_addk_i32 s19, 0x2000
	s_waitcnt vmcnt(0)
	s_add_u32 s44, s44, 0x80
	s_addc_u32 s45, s45, 0
	s_cmpk_eq_i32 s44, 0x780
	s_waitcnt vmcnt(0)
	s_barrier
	s_cbranch_scc0 .LBB0_226
	s_andn2_b64 vcc, exec, s[42:43]
	s_cbranch_vccnz .LBB0_229
	v_lshl_add_u64 v[66:67], v[90:91], 0, s[46:47]
	v_readfirstlane_b32 s0, v138
	v_lshl_add_u64 v[68:69], v[66:67], 0, v[114:115]
	v_lshl_add_u64 v[74:75], v[92:93], 0, s[52:53]
	s_mov_b32 m0, s0
	v_readfirstlane_b32 s0, v139
	v_lshl_add_u64 v[76:77], v[74:75], 0, v[120:121]
	v_lshl_add_u64 v[78:79], v[74:75], 0, v[118:119]
	v_lshl_add_u64 v[80:81], v[74:75], 0, v[116:117]
	v_lshl_add_u64 v[74:75], v[74:75], 0, v[114:115]
	global_load_lds_dwordx4 v[68:69], off
	s_mov_b32 m0, s0
	v_readfirstlane_b32 s0, v140
	v_lshl_add_u64 v[70:71], v[66:67], 0, v[116:117]
	global_load_lds_dwordx4 v[74:75], off
	s_mov_b32 m0, s0
	v_readfirstlane_b32 s0, v141
	global_load_lds_dwordx4 v[70:71], off
	s_mov_b32 m0, s0
	v_readfirstlane_b32 s0, v142
	v_lshl_add_u64 v[72:73], v[66:67], 0, v[118:119]
	global_load_lds_dwordx4 v[80:81], off
	s_mov_b32 m0, s0
	v_readfirstlane_b32 s0, v143
	global_load_lds_dwordx4 v[72:73], off
	s_mov_b32 m0, s0
	v_readfirstlane_b32 s0, v144
	v_lshl_add_u64 v[66:67], v[66:67], 0, v[120:121]
	global_load_lds_dwordx4 v[78:79], off
	s_mov_b32 m0, s0
	v_readfirstlane_b32 s0, v145
	global_load_lds_dwordx4 v[66:67], off
	s_mov_b32 m0, s0
	s_nop 0
	global_load_lds_dwordx4 v[76:77], off
.LBB0_229:
	v_add_u32_e32 v0, v151, v157
	ds_read_b128 v[66:69], v0 offset:16384
	ds_read_b128 v[70:73], v0 offset:18432
	ds_read_b128 v[74:77], v0 offset:20480
	ds_read_b128 v[78:81], v0 offset:22528
	v_add_u32_e32 v0, v152, v157
	ds_read_b128 v[82:85], v0 offset:49152
	ds_read_b128 v[86:89], v0 offset:51200
	ds_read_b128 v[122:125], v0 offset:53248
	ds_read_b128 v[126:129], v0 offset:55296
	v_add_u32_e32 v0, v151, v158
	ds_read_b128 v[214:217], v0 offset:16384
	ds_read_b128 v[218:221], v0 offset:18432
	ds_read_b128 v[222:225], v0 offset:20480
	ds_read_b128 v[226:229], v0 offset:22528
	v_add_u32_e32 v0, v152, v158
	ds_read_b128 v[230:233], v0 offset:49152
	ds_read_b128 v[234:237], v0 offset:51200
	ds_read_b128 v[238:241], v0 offset:53248
	s_setprio 1
	s_waitcnt lgkmcnt(7)
	ds_read_b128 v[242:245], v0 offset:55296
	v_mfma_f32_16x16x32_bf16 v[2:5], v[82:85], v[66:69], v[2:5]
	v_mfma_f32_16x16x32_bf16 v[6:9], v[86:89], v[66:69], v[6:9]
	v_mfma_f32_16x16x32_bf16 v[10:13], v[122:125], v[66:69], v[10:13]
	v_mfma_f32_16x16x32_bf16 v[14:17], v[126:129], v[66:69], v[14:17]
	v_mfma_f32_16x16x32_bf16 v[18:21], v[82:85], v[70:73], v[18:21]
	v_mfma_f32_16x16x32_bf16 v[22:25], v[86:89], v[70:73], v[22:25]
	v_mfma_f32_16x16x32_bf16 v[26:29], v[122:125], v[70:73], v[26:29]
	v_mfma_f32_16x16x32_bf16 v[66:69], v[126:129], v[70:73], v[30:33]
	v_mfma_f32_16x16x32_bf16 v[70:73], v[82:85], v[74:77], v[34:37]
	v_mfma_f32_16x16x32_bf16 v[130:133], v[86:89], v[74:77], v[38:41]
	v_mfma_f32_16x16x32_bf16 v[134:137], v[122:125], v[74:77], v[42:45]
	v_mfma_f32_16x16x32_bf16 v[74:77], v[126:129], v[74:77], v[46:49]
	v_mfma_f32_16x16x32_bf16 v[82:85], v[82:85], v[78:81], v[50:53]
	v_mfma_f32_16x16x32_bf16 v[86:89], v[86:89], v[78:81], v[54:57]
	v_mfma_f32_16x16x32_bf16 v[122:125], v[122:125], v[78:81], v[58:61]
	v_mfma_f32_16x16x32_bf16 v[78:81], v[126:129], v[78:81], v[62:65]
	s_waitcnt lgkmcnt(0)
	v_mfma_f32_16x16x32_bf16 v[42:45], v[230:233], v[214:217], v[2:5]
	v_mfma_f32_16x16x32_bf16 v[46:49], v[234:237], v[214:217], v[6:9]
	v_mfma_f32_16x16x32_bf16 v[38:41], v[238:241], v[214:217], v[10:13]
	v_mfma_f32_16x16x32_bf16 v[62:65], v[242:245], v[214:217], v[14:17]
	v_mfma_f32_16x16x32_bf16 v[30:33], v[230:233], v[218:221], v[18:21]
	v_mfma_f32_16x16x32_bf16 v[34:37], v[234:237], v[218:221], v[22:25]
	v_mfma_f32_16x16x32_bf16 v[22:25], v[238:241], v[218:221], v[26:29]
	v_mfma_f32_16x16x32_bf16 v[54:57], v[242:245], v[218:221], v[66:69]
	v_mfma_f32_16x16x32_bf16 v[18:21], v[230:233], v[222:225], v[70:73]
	v_mfma_f32_16x16x32_bf16 v[26:29], v[234:237], v[222:225], v[130:133]
	v_mfma_f32_16x16x32_bf16 v[14:17], v[238:241], v[222:225], v[134:137]
	v_mfma_f32_16x16x32_bf16 v[50:53], v[242:245], v[222:225], v[74:77]
	v_mfma_f32_16x16x32_bf16 v[10:13], v[230:233], v[226:229], v[82:85]
	v_mfma_f32_16x16x32_bf16 v[58:61], v[234:237], v[226:229], v[86:89]
	v_mfma_f32_16x16x32_bf16 v[2:5], v[238:241], v[226:229], v[122:125]
	v_mfma_f32_16x16x32_bf16 v[6:9], v[242:245], v[226:229], v[78:81]
	s_setprio 0
	s_add_i32 s0, s3, 0xfffffe00
	s_cmpk_lt_u32 s0, 0x280
	s_cbranch_scc0 .LBB0_239
	s_cmpk_lt_u32 s3, 0x400
	s_cselect_b64 vcc, -1, 0
	s_and_b64 s[0:1], vcc, exec
	v_readlane_b32 s0, v252, 52
	v_readlane_b32 s12, v253, 0
	v_readlane_b32 s14, v253, 2
	v_readlane_b32 s1, v252, 53
	v_readlane_b32 s13, v253, 1
	v_readlane_b32 s15, v253, 3
	s_cselect_b32 s0, s12, s14
	s_cselect_b32 s1, s13, s15
	s_add_u32 s0, s0, s34
	s_addc_u32 s1, s1, s35
	v_lshlrev_b32_e32 v66, 2, v94
	global_load_dwordx4 v[78:81], v66, s[0:1]
	global_load_dwordx4 v[74:77], v66, s[0:1] offset:64
	global_load_dwordx4 v[70:73], v66, s[0:1] offset:128
	s_nop 0
	global_load_dwordx4 v[66:69], v66, s[0:1] offset:192
	v_mul_f32_e32 v123, v43, v43
	v_fmac_f32_e32 v123, v42, v42
	v_fmac_f32_e32 v123, v44, v44
	v_fmac_f32_e32 v123, v45, v45
	v_fmac_f32_e32 v123, v46, v46
	v_fmac_f32_e32 v123, v47, v47
	v_fmac_f32_e32 v123, v48, v48
	v_pk_mul_f32 v[84:85], v[38:39], v[38:39]
	v_fmac_f32_e32 v123, v49, v49
	v_add_f32_e32 v84, v84, v123
	v_pk_mul_f32 v[82:83], v[40:41], v[40:41]
	v_add_f32_e32 v84, v85, v84
	v_add_f32_e32 v82, v82, v84
	v_pk_mul_f32 v[88:89], v[62:63], v[62:63]
	v_add_f32_e32 v82, v83, v82
	v_add_f32_e32 v82, v88, v82
	v_cndmask_b32_e32 v0, 1.0, v199, vcc
	v_cmp_lt_i32_e32 vcc, v194, v192
	v_pk_mul_f32 v[86:87], v[64:65], v[64:65]
	v_add_f32_e32 v82, v89, v82
	v_cndmask_b32_e32 v122, v191, v194, vcc
	v_add_f32_e32 v82, v86, v82
	v_lshlrev_b32_e32 v159, 2, v122
	v_add_f32_e32 v83, v87, v82
	ds_bpermute_b32 v84, v159, v83
	v_cmp_lt_i32_e32 vcc, v193, v192
	v_mov_b32_e32 v82, v42
	v_add_u32_e32 v86, s40, v154
	v_cndmask_b32_e32 v85, v191, v193, vcc
	v_lshlrev_b32_e32 v161, 2, v85
	s_waitcnt lgkmcnt(0)
	v_add_f32_e32 v42, v83, v84
	ds_bpermute_b32 v87, v161, v42
	v_mov_b32_e32 v84, v38
	v_mov_b32_e32 v85, v63
	v_mov_b32_e32 v63, v39
	v_mov_b32_e32 v83, v47
	s_waitcnt lgkmcnt(0)
	v_add_f32_e32 v38, v42, v87
	v_fmamk_f32 v38, v38, 0x3c800000, v189
	v_mul_f32_e32 v39, 0x4b800000, v38
	v_cmp_gt_f32_e32 vcc, s33, v38
	v_or_b32_e32 v162, v86, v146
	v_bfe_u32 v160, v86, 6, 5
	v_cndmask_b32_e32 v38, v38, v39, vcc
	v_rsq_f32_e32 v38, v38
	v_mov_b32_e32 v47, v43
	v_readlane_b32 s2, v252, 54
	v_readlane_b32 s3, v252, 55
	v_mul_f32_e32 v39, 0x45800000, v38
	v_cndmask_b32_e32 v38, v38, v39, vcc
	v_mul_f32_e32 v38, v0, v38
	v_cmp_gt_i32_e32 vcc, s74, v162
	v_readlane_b32 s4, v252, 56
	v_readlane_b32 s5, v252, 57
	v_readlane_b32 s6, v252, 58
	v_readlane_b32 s7, v252, 59
	v_readlane_b32 s8, v252, 60
	v_readlane_b32 s9, v252, 61
	v_readlane_b32 s10, v252, 62
	v_readlane_b32 s11, v252, 63
	s_waitcnt vmcnt(0)
	v_mul_f32_e32 v39, v80, v38
	v_mov_b32_e32 v125, v75
	v_mov_b32_e32 v75, v79
	v_mov_b32_e32 v124, v78
	v_mul_f32_e32 v86, v76, v38
	v_mov_b32_e32 v122, v81
	v_mov_b32_e32 v123, v77
	v_mov_b32_e32 v78, v70
	v_mov_b32_e32 v79, v67
	v_mov_b32_e32 v67, v71
	v_pk_mul_f32 v[70:71], v[74:75], v[38:39] op_sel_hi:[1,0]
	v_mul_f32_e32 v44, v44, v39
	v_pk_mul_f32 v[42:43], v[124:125], v[38:39] op_sel_hi:[1,0]
	v_mul_f32_e32 v88, v48, v86
	v_pk_mul_f32 v[86:87], v[122:123], v[38:39] op_sel_hi:[1,0]
	v_pk_mul_f32 v[126:127], v[78:79], v[38:39] op_sel_hi:[1,0]
	v_pk_mul_f32 v[128:129], v[66:67], v[38:39] op_sel_hi:[1,0]
	v_pk_mul_f32 v[136:137], v[46:47], v[70:71]
	v_mul_f32_e32 v39, v68, v38
	v_mov_b32_e32 v70, v73
	v_mov_b32_e32 v71, v69
	v_mul_f32_e32 v77, v72, v38
	v_mov_b32_e32 v48, v45
	v_pk_mul_f32 v[132:133], v[82:83], v[42:43]
	v_pk_mul_f32 v[126:127], v[84:85], v[126:127]
	v_pk_mul_f32 v[130:131], v[62:63], v[128:129]
	v_mul_f32_e32 v84, v64, v39
	v_pk_mul_f32 v[38:39], v[70:71], v[38:39] op_sel_hi:[1,0]
	v_mov_b32_e32 v64, v41
	v_pk_mul_f32 v[134:135], v[48:49], v[86:87]
	v_mov_b32_e32 v86, v136
	v_mov_b32_e32 v87, v133
	v_pk_mul_f32 v[128:129], v[64:65], v[38:39]
	v_mov_b32_e32 v82, v130
	v_mov_b32_e32 v83, v127
	v_mov_b32_e32 v89, v135
	v_mov_b32_e32 v85, v129
	v_mov_b64_e32 v[46:47], v[86:87]
	v_mov_b64_e32 v[62:63], v[82:83]
	v_mul_f32_e32 v40, v40, v77
	v_mov_b32_e32 v42, v132
	v_mov_b32_e32 v43, v137
	v_mov_b32_e32 v45, v134
	v_mov_b32_e32 v38, v126
	v_mov_b32_e32 v39, v131
	v_mov_b32_e32 v41, v128
	v_lshlrev_b32_e32 v69, 3, v94
	v_mov_b64_e32 v[48:49], v[88:89]
	v_mov_b64_e32 v[64:65], v[84:85]
	s_and_saveexec_b64 s[42:43], vcc
	s_cbranch_execz .LBB0_232
	v_lshl_or_b32 v38, v160, 7, v69
	global_load_dwordx4 v[46:49], v38, s[16:17] offset:16
	global_load_dwordx4 v[62:65], v38, s[16:17]
	s_waitcnt vmcnt(1)
	v_mul_f32_e32 v164, v44, v47
	s_waitcnt vmcnt(0)
	v_mov_b32_e32 v42, v62
	v_mov_b32_e32 v43, v65
	v_pk_mul_f32 v[82:83], v[136:137], v[42:43]
	v_mov_b32_e32 v42, v136
	v_mov_b32_e32 v43, v133
	v_mov_b32_e32 v86, v63
	v_mov_b32_e32 v87, v65
	v_mov_b32_e32 v38, v63
	v_mov_b32_e32 v39, v64
	v_pk_mul_f32 v[42:43], v[42:43], v[86:87]
	v_mov_b32_e32 v63, v64
	v_mul_f32_e32 v64, v44, v46
	v_mul_f32_e32 v86, v88, v47
	v_mul_f32_e32 v88, v88, v46
	v_pk_mul_f32 v[44:45], v[134:135], v[48:49]
	v_pk_mul_f32 v[46:47], v[134:135], v[48:49] op_sel:[1,0] op_sel_hi:[0,1]
	v_mov_b32_e32 v136, v132
	v_mov_b32_e32 v65, v44
	v_mov_b32_e32 v87, v45
	v_mov_b32_e32 v89, v46
	v_mov_b32_e32 v165, v47
	v_pk_fma_f32 v[42:43], v[136:137], v[62:63], v[42:43] neg_lo:[0,0,1] neg_hi:[0,0,1]
	v_pk_add_f32 v[44:45], v[64:65], v[86:87] neg_lo:[0,1] neg_hi:[0,1]
	v_pk_add_f32 v[48:49], v[88:89], v[164:165]
	global_load_dwordx4 v[62:65], v[96:97], off offset:16
	global_load_dwordx4 v[86:89], v[96:97], off
	v_pk_fma_f32 v[46:47], v[132:133], v[38:39], v[82:83]
	s_waitcnt vmcnt(1)
	v_mul_f32_e32 v136, v40, v63
	s_waitcnt vmcnt(0)
	v_mov_b32_e32 v38, v86
	v_mov_b32_e32 v39, v89
	v_pk_mul_f32 v[132:133], v[130:131], v[38:39]
	v_mov_b32_e32 v38, v130
	v_mov_b32_e32 v39, v127
	v_mov_b32_e32 v134, v87
	v_mov_b32_e32 v135, v89
	v_mov_b32_e32 v82, v87
	v_mov_b32_e32 v83, v88
	v_pk_mul_f32 v[38:39], v[38:39], v[134:135]
	v_mov_b32_e32 v87, v88
	v_mul_f32_e32 v88, v40, v62
	v_mul_f32_e32 v134, v84, v63
	v_mul_f32_e32 v84, v84, v62
	v_pk_mul_f32 v[40:41], v[128:129], v[64:65]
	v_pk_mul_f32 v[62:63], v[128:129], v[64:65] op_sel:[1,0] op_sel_hi:[0,1]
	v_mov_b32_e32 v130, v126
	v_mov_b32_e32 v89, v40
	v_mov_b32_e32 v135, v41
	v_mov_b32_e32 v85, v62
	v_mov_b32_e32 v137, v63
	v_pk_fma_f32 v[38:39], v[130:131], v[86:87], v[38:39] neg_lo:[0,0,1] neg_hi:[0,0,1]
	v_pk_add_f32 v[40:41], v[88:89], v[134:135] neg_lo:[0,1] neg_hi:[0,1]
	v_pk_fma_f32 v[62:63], v[126:127], v[82:83], v[132:133]
	v_pk_add_f32 v[64:65], v[84:85], v[136:137]

.LBB0_888:
	v_add_u32_e32 v95, v125, v128
	ds_read_b128 v[96:99], v95 offset:16384
	ds_read_b128 v[100:103], v95 offset:18432
	ds_read_b128 v[104:107], v95 offset:20480
	ds_read_b128 v[108:111], v95 offset:22528
	v_add_u32_e32 v95, v126, v128
	ds_read_b128 v[130:133], v95 offset:49152
	ds_read_b128 v[134:137], v95 offset:51200
	ds_read_b128 v[138:141], v95 offset:53248
	ds_read_b128 v[142:145], v95 offset:55296
	v_add_u32_e32 v95, v125, v129
	ds_read_b128 v[214:217], v95 offset:16384
	ds_read_b128 v[218:221], v95 offset:18432
	ds_read_b128 v[222:225], v95 offset:20480
	ds_read_b128 v[226:229], v95 offset:22528
	v_add_u32_e32 v95, v126, v129
	ds_read_b128 v[230:233], v95 offset:49152
	ds_read_b128 v[234:237], v95 offset:51200
	ds_read_b128 v[238:241], v95 offset:53248
	s_setprio 1
	s_waitcnt lgkmcnt(7)
	ds_read_b128 v[242:245], v95 offset:55296
	v_mfma_f32_16x16x32_bf16 v[2:5], v[130:133], v[96:99], v[2:5]
	v_mfma_f32_16x16x32_bf16 v[6:9], v[134:137], v[96:99], v[6:9]
	v_mfma_f32_16x16x32_bf16 v[10:13], v[138:141], v[96:99], v[10:13]
	v_mfma_f32_16x16x32_bf16 v[14:17], v[142:145], v[96:99], v[14:17]
	v_mfma_f32_16x16x32_bf16 v[18:21], v[130:133], v[100:103], v[18:21]
	v_mfma_f32_16x16x32_bf16 v[22:25], v[134:137], v[100:103], v[22:25]
	v_mfma_f32_16x16x32_bf16 v[26:29], v[138:141], v[100:103], v[26:29]
	v_mfma_f32_16x16x32_bf16 v[30:33], v[142:145], v[100:103], v[30:33]
	v_mfma_f32_16x16x32_bf16 v[34:37], v[130:133], v[104:107], v[34:37]
	v_mfma_f32_16x16x32_bf16 v[38:41], v[134:137], v[104:107], v[38:41]
	v_mfma_f32_16x16x32_bf16 v[96:99], v[138:141], v[104:107], v[42:45]
	v_mfma_f32_16x16x32_bf16 v[100:103], v[142:145], v[104:107], v[46:49]
	v_mfma_f32_16x16x32_bf16 v[50:53], v[130:133], v[108:111], v[50:53]
	v_mfma_f32_16x16x32_bf16 v[54:57], v[134:137], v[108:111], v[54:57]
	v_mfma_f32_16x16x32_bf16 v[58:61], v[138:141], v[108:111], v[58:61]
	v_mfma_f32_16x16x32_bf16 v[62:65], v[142:145], v[108:111], v[62:65]
	s_waitcnt lgkmcnt(0)
	v_mfma_f32_16x16x32_bf16 v[146:149], v[230:233], v[214:217], v[2:5]
	v_mfma_f32_16x16x32_bf16 v[6:9], v[234:237], v[214:217], v[6:9]
	v_mfma_f32_16x16x32_bf16 v[150:153], v[238:241], v[214:217], v[10:13]
	v_mfma_f32_16x16x32_bf16 v[154:157], v[242:245], v[214:217], v[14:17]
	v_mfma_f32_16x16x32_bf16 v[158:161], v[230:233], v[218:221], v[18:21]
	v_mfma_f32_16x16x32_bf16 v[162:165], v[234:237], v[218:221], v[22:25]
	v_mfma_f32_16x16x32_bf16 v[166:169], v[238:241], v[218:221], v[26:29]
	v_mfma_f32_16x16x32_bf16 v[176:179], v[242:245], v[218:221], v[30:33]
	v_mfma_f32_16x16x32_bf16 v[46:49], v[230:233], v[222:225], v[34:37]
	v_mfma_f32_16x16x32_bf16 v[42:45], v[234:237], v[222:225], v[38:41]
	v_mfma_f32_16x16x32_bf16 v[38:41], v[238:241], v[222:225], v[96:99]
	v_mfma_f32_16x16x32_bf16 v[22:25], v[242:245], v[222:225], v[100:103]
	v_mfma_f32_16x16x32_bf16 v[18:21], v[230:233], v[226:229], v[50:53]
	v_mfma_f32_16x16x32_bf16 v[14:17], v[234:237], v[226:229], v[54:57]
	v_mfma_f32_16x16x32_bf16 v[10:13], v[238:241], v[226:229], v[58:61]
	v_mfma_f32_16x16x32_bf16 v[2:5], v[242:245], v[226:229], v[62:65]
	s_setprio 0
	s_min_i32 s0, s40, 0x4000
	s_ashr_i32 s0, s0, 11
	s_add_i32 s0, s0, s25
	s_mul_hi_i32 s1, s0, 0x6000
	s_mulk_i32 s0, 0x6000
	s_add_u32 s19, s94, s0
	s_addc_u32 s27, s95, s1
	s_lshl_b64 s[0:1], s[42:43], 2
	v_add_u32_e32 v28, s40, v127
	s_add_u32 s26, s19, s0
	v_ashrrev_i32_e32 v29, 31, v28
	s_addc_u32 s27, s27, s1
	v_lshlrev_b64 v[28:29], 12, v[28:29]
	v_lshl_add_u64 v[26:27], s[26:27], 0, v[0:1]
	v_mov_b32_e32 v95, v1
	v_lshl_add_u64 v[28:29], s[94:95], 0, v[28:29]
	v_lshl_add_u64 v[26:27], v[26:27], 0, v[94:95]
	s_mov_b64 s[26:27], 0x13582000
	v_lshl_add_u64 v[28:29], v[28:29], 0, s[0:1]
	s_mov_b32 s0, 0x13582000
	v_lshl_add_u64 v[52:53], v[26:27], 0, s[26:27]
	v_add_co_u32_e32 v26, vcc, s0, v26
	v_lshl_add_u64 v[28:29], v[28:29], 0, v[0:1]
	s_nop 0
	v_addc_co_u32_e32 v27, vcc, 0, v27, vcc
	v_lshl_add_u64 v[50:51], v[28:29], 0, v[94:95]
	global_load_dwordx4 v[26:29], v[26:27], off
	s_nop 0
	global_load_dwordx4 v[30:33], v[50:51], off
	v_add_co_u32_e32 v56, vcc, s96, v50
	s_mov_b32 s0, 0x30000
	s_nop 0
	v_addc_co_u32_e32 v57, vcc, 0, v51, vcc
	s_waitcnt vmcnt(0)
	v_pk_fma_f32 v[30:31], v[146:147], v[26:27], v[30:31]
	v_pk_fma_f32 v[32:33], v[148:149], v[28:29], v[32:33]
	global_store_dwordx4 v[50:51], v[30:33], off
	global_load_dwordx4 v[30:33], v[52:53], off offset:64
	s_nop 0
	global_load_dwordx4 v[34:37], v[50:51], off offset:64
	s_waitcnt vmcnt(0)
	v_pk_fma_f32 v[6:7], v[6:7], v[30:31], v[34:35]
	v_pk_fma_f32 v[8:9], v[8:9], v[32:33], v[36:37]
	global_store_dwordx4 v[50:51], v[6:9], off offset:64
	global_load_dwordx4 v[34:37], v[52:53], off offset:128
	s_nop 0
	global_load_dwordx4 v[6:9], v[50:51], off offset:128
	s_waitcnt vmcnt(0)
	v_pk_fma_f32 v[6:7], v[150:151], v[34:35], v[6:7]
	v_pk_fma_f32 v[8:9], v[152:153], v[36:37], v[8:9]
	global_store_dwordx4 v[50:51], v[6:9], off offset:128
	global_load_dwordx4 v[6:9], v[52:53], off offset:192
	s_nop 0
	global_load_dwordx4 v[52:55], v[50:51], off offset:192
	s_waitcnt vmcnt(0)
	v_pk_fma_f32 v[52:53], v[154:155], v[6:7], v[52:53]
	v_pk_fma_f32 v[54:55], v[156:157], v[8:9], v[54:55]
	global_store_dwordx4 v[50:51], v[52:55], off offset:192
	global_load_dwordx4 v[52:55], v[56:57], off
	s_waitcnt vmcnt(0)
	v_pk_fma_f32 v[52:53], v[158:159], v[26:27], v[52:53]
	v_pk_fma_f32 v[54:55], v[160:161], v[28:29], v[54:55]
	global_store_dwordx4 v[56:57], v[52:55], off
	global_load_dwordx4 v[52:55], v[56:57], off offset:64
	s_waitcnt vmcnt(0)
	v_pk_fma_f32 v[52:53], v[162:163], v[30:31], v[52:53]
	v_pk_fma_f32 v[54:55], v[164:165], v[32:33], v[54:55]
	global_store_dwordx4 v[56:57], v[52:55], off offset:64
	global_load_dwordx4 v[52:55], v[56:57], off offset:128
	s_waitcnt vmcnt(0)
	v_pk_fma_f32 v[52:53], v[166:167], v[34:35], v[52:53]
	v_pk_fma_f32 v[54:55], v[168:169], v[36:37], v[54:55]
	global_store_dwordx4 v[56:57], v[52:55], off offset:128
	global_load_dwordx4 v[52:55], v[56:57], off offset:192
	s_waitcnt vmcnt(0)
	v_pk_fma_f32 v[52:53], v[176:177], v[6:7], v[52:53]
	v_pk_fma_f32 v[54:55], v[178:179], v[8:9], v[54:55]
	global_store_dwordx4 v[56:57], v[52:55], off offset:192
	v_add_co_u32_e32 v56, vcc, s24, v50
	s_nop 1
	v_addc_co_u32_e32 v57, vcc, 0, v51, vcc
	global_load_dwordx4 v[52:55], v[56:57], off
	s_waitcnt vmcnt(0)
	v_pk_fma_f32 v[46:47], v[46:47], v[26:27], v[52:53]
	v_pk_fma_f32 v[48:49], v[48:49], v[28:29], v[54:55]
	global_store_dwordx4 v[56:57], v[46:49], off
	global_load_dwordx4 v[46:49], v[56:57], off offset:64
	s_waitcnt vmcnt(0)
	v_pk_fma_f32 v[42:43], v[42:43], v[30:31], v[46:47]
	v_pk_fma_f32 v[44:45], v[44:45], v[32:33], v[48:49]
	global_store_dwordx4 v[56:57], v[42:45], off offset:64
	global_load_dwordx4 v[42:45], v[56:57], off offset:128
	s_waitcnt vmcnt(0)
	v_pk_fma_f32 v[38:39], v[38:39], v[34:35], v[42:43]
	v_pk_fma_f32 v[40:41], v[40:41], v[36:37], v[44:45]
	global_store_dwordx4 v[56:57], v[38:41], off offset:128
	global_load_dwordx4 v[38:41], v[56:57], off offset:192
	s_waitcnt vmcnt(0)
	v_pk_fma_f32 v[22:23], v[22:23], v[6:7], v[38:39]
	v_pk_fma_f32 v[24:25], v[24:25], v[8:9], v[40:41]
	global_store_dwordx4 v[56:57], v[22:25], off offset:192
	s_nop 1
	v_add_co_u32_e32 v22, vcc, s0, v50
	s_mov_b32 s0, s3
	s_nop 0
	v_addc_co_u32_e32 v23, vcc, 0, v51, vcc
	global_load_dwordx4 v[38:41], v[22:23], off
	s_and_b64 vcc, exec, s[34:35]
	s_waitcnt vmcnt(0)
	v_pk_fma_f32 v[18:19], v[18:19], v[26:27], v[38:39]
	v_pk_fma_f32 v[20:21], v[20:21], v[28:29], v[40:41]
	global_store_dwordx4 v[22:23], v[18:21], off
	global_load_dwordx4 v[18:21], v[22:23], off offset:64
	s_waitcnt vmcnt(0)
	v_pk_fma_f32 v[14:15], v[14:15], v[30:31], v[18:19]
	v_pk_fma_f32 v[16:17], v[16:17], v[32:33], v[20:21]
	global_store_dwordx4 v[22:23], v[14:17], off offset:64
	global_load_dwordx4 v[14:17], v[22:23], off offset:128
	s_waitcnt vmcnt(0)
	v_pk_fma_f32 v[10:11], v[10:11], v[34:35], v[14:15]
	v_pk_fma_f32 v[12:13], v[12:13], v[36:37], v[16:17]
	global_store_dwordx4 v[22:23], v[10:13], off offset:128
	global_load_dwordx4 v[10:13], v[22:23], off offset:192
	s_waitcnt vmcnt(0)
	v_pk_fma_f32 v[2:3], v[2:3], v[6:7], v[10:11]
	v_pk_fma_f32 v[4:5], v[4:5], v[8:9], v[12:13]
	global_store_dwordx4 v[22:23], v[2:5], off offset:192
	s_cbranch_vccnz .LBB0_895

.LBB0_892:
	s_and_b32 s0, s19, 0x2000
	s_xor_b32 s1, s0, 0x2000
	s_lshl_b32 s0, s0, 1
	v_add_u32_e32 v95, s0, v125
	v_add_u32_e32 v162, s0, v126
	v_add_u32_e32 v142, v95, v128
	v_add_u32_e32 v158, v162, v128
	ds_read_b128 v[130:133], v142
	ds_read_b128 v[134:137], v142 offset:2048
	ds_read_b128 v[138:141], v142 offset:4096
	ds_read_b128 v[142:145], v142 offset:6144
	ds_read_b128 v[146:149], v158 offset:32768
	ds_read_b128 v[150:153], v158 offset:34816
	ds_read_b128 v[154:157], v158 offset:36864
	ds_read_b128 v[158:161], v158 offset:38912
	v_lshl_add_u32 v250, s1, 1, v112
	v_lshl_add_u32 v255, v121, 1, v250
	v_add_u32_e32 v180, 0x8000, v255
	v_readfirstlane_b32 s1, v255
	v_lshl_add_u64 v[246:247], v[96:97], 0, s[46:47]
	s_mov_b32 m0, s1
	v_readfirstlane_b32 s1, v180
	v_lshl_add_u32 v255, v122, 1, v250
	v_lshl_add_u64 v[248:249], v[104:105], 0, s[46:47]
	global_load_lds_dwordx4 v[246:247], off
	s_mov_b32 m0, s1
	v_add_u32_e32 v180, 0x8000, v255
	v_readfirstlane_b32 s1, v255
	global_load_lds_dwordx4 v[248:249], off
	v_lshl_add_u64 v[246:247], v[98:99], 0, s[46:47]
	s_mov_b32 m0, s1
	v_readfirstlane_b32 s1, v180
	v_lshl_add_u32 v255, v123, 1, v250
	v_lshl_add_u64 v[248:249], v[106:107], 0, s[46:47]
	global_load_lds_dwordx4 v[246:247], off
	s_mov_b32 m0, s1
	v_add_u32_e32 v180, 0x8000, v255
	v_readfirstlane_b32 s1, v255
	global_load_lds_dwordx4 v[248:249], off
	v_lshl_add_u64 v[246:247], v[100:101], 0, s[46:47]
	s_mov_b32 m0, s1
	v_readfirstlane_b32 s1, v180
	v_lshl_add_u32 v250, v124, 1, v250
	v_lshl_add_u64 v[248:249], v[108:109], 0, s[46:47]
	global_load_lds_dwordx4 v[246:247], off
	s_mov_b32 m0, s1
	v_add_u32_e32 v255, 0x8000, v250
	v_readfirstlane_b32 s1, v250
	global_load_lds_dwordx4 v[248:249], off
	v_lshl_add_u64 v[246:247], v[102:103], 0, s[46:47]
	s_mov_b32 m0, s1
	v_readfirstlane_b32 s1, v255
	v_lshl_add_u64 v[248:249], v[110:111], 0, s[46:47]
	global_load_lds_dwordx4 v[246:247], off
	s_mov_b32 m0, s1
	global_load_lds_dwordx4 v[248:249], off
	v_add_u32_e32 v95, v95, v129
	ds_read_b128 v[214:217], v95
	ds_read_b128 v[218:221], v95 offset:2048
	ds_read_b128 v[222:225], v95 offset:4096
	ds_read_b128 v[226:229], v95 offset:6144
	v_add_u32_e32 v95, v162, v129
	ds_read_b128 v[230:233], v95 offset:32768
	ds_read_b128 v[234:237], v95 offset:34816
	ds_read_b128 v[238:241], v95 offset:36864
	s_setprio 1
	s_waitcnt lgkmcnt(7)
	ds_read_b128 v[242:245], v95 offset:38912
	v_mfma_f32_16x16x32_bf16 v[2:5], v[146:149], v[130:133], v[2:5]
	v_mfma_f32_16x16x32_bf16 v[6:9], v[150:153], v[130:133], v[6:9]
	v_mfma_f32_16x16x32_bf16 v[10:13], v[154:157], v[130:133], v[10:13]
	v_mfma_f32_16x16x32_bf16 v[14:17], v[158:161], v[130:133], v[14:17]
	v_mfma_f32_16x16x32_bf16 v[18:21], v[146:149], v[134:137], v[18:21]
	v_mfma_f32_16x16x32_bf16 v[22:25], v[150:153], v[134:137], v[22:25]
	v_mfma_f32_16x16x32_bf16 v[26:29], v[154:157], v[134:137], v[26:29]
	v_mfma_f32_16x16x32_bf16 v[30:33], v[158:161], v[134:137], v[30:33]
	v_mfma_f32_16x16x32_bf16 v[34:37], v[146:149], v[138:141], v[34:37]
	v_mfma_f32_16x16x32_bf16 v[38:41], v[150:153], v[138:141], v[38:41]
	v_mfma_f32_16x16x32_bf16 v[42:45], v[154:157], v[138:141], v[42:45]
	v_mfma_f32_16x16x32_bf16 v[46:49], v[158:161], v[138:141], v[46:49]
	v_mfma_f32_16x16x32_bf16 v[50:53], v[146:149], v[142:145], v[50:53]
	v_mfma_f32_16x16x32_bf16 v[54:57], v[150:153], v[142:145], v[54:57]
	v_mfma_f32_16x16x32_bf16 v[58:61], v[154:157], v[142:145], v[58:61]
	v_mfma_f32_16x16x32_bf16 v[62:65], v[158:161], v[142:145], v[62:65]
	s_waitcnt lgkmcnt(0)
	v_mfma_f32_16x16x32_bf16 v[2:5], v[230:233], v[214:217], v[2:5]
	v_mfma_f32_16x16x32_bf16 v[6:9], v[234:237], v[214:217], v[6:9]
	v_mfma_f32_16x16x32_bf16 v[10:13], v[238:241], v[214:217], v[10:13]
	v_mfma_f32_16x16x32_bf16 v[14:17], v[242:245], v[214:217], v[14:17]
	v_mfma_f32_16x16x32_bf16 v[18:21], v[230:233], v[218:221], v[18:21]
	v_mfma_f32_16x16x32_bf16 v[22:25], v[234:237], v[218:221], v[22:25]
	v_mfma_f32_16x16x32_bf16 v[26:29], v[238:241], v[218:221], v[26:29]
	v_mfma_f32_16x16x32_bf16 v[30:33], v[242:245], v[218:221], v[30:33]
	v_mfma_f32_16x16x32_bf16 v[34:37], v[230:233], v[222:225], v[34:37]
	v_mfma_f32_16x16x32_bf16 v[38:41], v[234:237], v[222:225], v[38:41]
	v_mfma_f32_16x16x32_bf16 v[42:45], v[238:241], v[222:225], v[42:45]
	v_mfma_f32_16x16x32_bf16 v[46:49], v[242:245], v[222:225], v[46:49]
	v_mfma_f32_16x16x32_bf16 v[50:53], v[230:233], v[226:229], v[50:53]
	v_mfma_f32_16x16x32_bf16 v[54:57], v[234:237], v[226:229], v[54:57]
	v_mfma_f32_16x16x32_bf16 v[58:61], v[238:241], v[226:229], v[58:61]
	v_mfma_f32_16x16x32_bf16 v[62:65], v[242:245], v[226:229], v[62:65]
	s_setprio 0
	s_waitcnt vmcnt(0)
	s_add_u32 s46, s46, 0x80
	s_addc_u32 s47, s47, 0
	s_addk_i32 s19, 0x2000
	s_cmpk_eq_i32 s46, 0x780
	s_waitcnt vmcnt(0)
	s_barrier
	s_cbranch_scc0 .LBB0_892
	s_andn2_b64 vcc, exec, s[44:45]
	s_cbranch_vccnz .LBB0_888
	v_lshl_add_u64 v[96:97], s[56:57], 1, v[66:67]
	v_readfirstlane_b32 s0, v113
	v_lshl_add_u64 v[98:99], v[96:97], 0, v[86:87]
	v_lshl_add_u64 v[104:105], s[52:53], 1, v[68:69]
	s_mov_b32 m0, s0
	v_readfirstlane_b32 s0, v114
	v_lshl_add_u64 v[106:107], v[104:105], 0, v[92:93]
	v_lshl_add_u64 v[108:109], v[104:105], 0, v[90:91]
	v_lshl_add_u64 v[110:111], v[104:105], 0, v[88:89]
	v_lshl_add_u64 v[104:105], v[104:105], 0, v[86:87]
	global_load_lds_dwordx4 v[98:99], off
	s_mov_b32 m0, s0
	v_readfirstlane_b32 s0, v115
	v_lshl_add_u64 v[100:101], v[96:97], 0, v[88:89]
	global_load_lds_dwordx4 v[104:105], off
	s_mov_b32 m0, s0
	v_readfirstlane_b32 s0, v116
	global_load_lds_dwordx4 v[100:101], off
	s_mov_b32 m0, s0
	v_readfirstlane_b32 s0, v117
	v_lshl_add_u64 v[102:103], v[96:97], 0, v[90:91]
	global_load_lds_dwordx4 v[110:111], off
	s_mov_b32 m0, s0
	v_readfirstlane_b32 s0, v118
	global_load_lds_dwordx4 v[102:103], off
	s_mov_b32 m0, s0
	v_readfirstlane_b32 s0, v119
	v_lshl_add_u64 v[96:97], v[96:97], 0, v[92:93]
	global_load_lds_dwordx4 v[108:109], off
	s_mov_b32 m0, s0
	v_readfirstlane_b32 s0, v120
	global_load_lds_dwordx4 v[96:97], off
	s_mov_b32 m0, s0
	s_nop 0
	global_load_lds_dwordx4 v[106:107], off
	s_branch .LBB0_888

.LBB0_996:
	v_add_u32_e32 v0, v123, v127
	ds_read_b128 v[94:97], v0 offset:16384
	ds_read_b128 v[98:101], v0 offset:18432
	ds_read_b128 v[102:105], v0 offset:20480
	ds_read_b128 v[106:109], v0 offset:22528
	v_add_u32_e32 v0, v124, v127
	ds_read_b128 v[130:133], v0 offset:49152
	ds_read_b128 v[134:137], v0 offset:51200
	ds_read_b128 v[138:141], v0 offset:53248
	ds_read_b128 v[142:145], v0 offset:55296
	v_add_u32_e32 v0, v123, v128
	s_nop 0
	ds_read_b128 v[214:217], v0 offset:16384
	ds_read_b128 v[218:221], v0 offset:18432
	ds_read_b128 v[222:225], v0 offset:20480
	ds_read_b128 v[226:229], v0 offset:22528
	v_add_u32_e32 v0, v124, v128
	ds_read_b128 v[230:233], v0 offset:49152
	ds_read_b128 v[234:237], v0 offset:51200
	ds_read_b128 v[238:241], v0 offset:53248
	s_setprio 1
	s_waitcnt lgkmcnt(7)
	ds_read_b128 v[242:245], v0 offset:55296
	v_mfma_f32_16x16x32_bf16 v[62:65], v[130:133], v[94:97], v[62:65]
	v_mfma_f32_16x16x32_bf16 v[58:61], v[134:137], v[94:97], v[58:61]
	v_mfma_f32_16x16x32_bf16 v[54:57], v[138:141], v[94:97], v[54:57]
	v_mfma_f32_16x16x32_bf16 v[94:97], v[142:145], v[94:97], v[50:53]
	v_mfma_f32_16x16x32_bf16 v[46:49], v[130:133], v[98:101], v[46:49]
	v_mfma_f32_16x16x32_bf16 v[146:149], v[134:137], v[98:101], v[42:45]
	v_mfma_f32_16x16x32_bf16 v[38:41], v[138:141], v[98:101], v[38:41]
	v_mfma_f32_16x16x32_bf16 v[98:101], v[142:145], v[98:101], v[34:37]
	v_mfma_f32_16x16x32_bf16 v[30:33], v[130:133], v[102:105], v[30:33]
	v_mfma_f32_16x16x32_bf16 v[150:153], v[134:137], v[102:105], v[26:29]
	v_mfma_f32_16x16x32_bf16 v[22:25], v[138:141], v[102:105], v[22:25]
	v_mfma_f32_16x16x32_bf16 v[102:105], v[142:145], v[102:105], v[18:21]
	v_mfma_f32_16x16x32_bf16 v[14:17], v[130:133], v[106:109], v[14:17]
	v_mfma_f32_16x16x32_bf16 v[130:133], v[134:137], v[106:109], v[10:13]
	v_mfma_f32_16x16x32_bf16 v[6:9], v[138:141], v[106:109], v[6:9]
	v_mfma_f32_16x16x32_bf16 v[106:109], v[142:145], v[106:109], v[2:5]
	s_waitcnt lgkmcnt(0)
	v_mfma_f32_16x16x32_bf16 v[62:65], v[230:233], v[214:217], v[62:65]
	v_mfma_f32_16x16x32_bf16 v[166:169], v[234:237], v[214:217], v[58:61]
	v_mfma_f32_16x16x32_bf16 v[50:53], v[238:241], v[214:217], v[54:57]
	v_mfma_f32_16x16x32_bf16 v[54:57], v[242:245], v[214:217], v[94:97]
	v_mfma_f32_16x16x32_bf16 v[42:45], v[230:233], v[218:221], v[46:49]
	v_mfma_f32_16x16x32_bf16 v[46:49], v[234:237], v[218:221], v[146:149]
	v_mfma_f32_16x16x32_bf16 v[34:37], v[238:241], v[218:221], v[38:41]
	v_mfma_f32_16x16x32_bf16 v[38:41], v[242:245], v[218:221], v[98:101]
	v_mfma_f32_16x16x32_bf16 v[26:29], v[230:233], v[222:225], v[30:33]
	v_mfma_f32_16x16x32_bf16 v[30:33], v[234:237], v[222:225], v[150:153]
	v_mfma_f32_16x16x32_bf16 v[18:21], v[238:241], v[222:225], v[22:25]
	v_mfma_f32_16x16x32_bf16 v[22:25], v[242:245], v[222:225], v[102:105]
	v_mfma_f32_16x16x32_bf16 v[10:13], v[230:233], v[226:229], v[14:17]
	v_mfma_f32_16x16x32_bf16 v[14:17], v[234:237], v[226:229], v[130:133]
	v_mfma_f32_16x16x32_bf16 v[2:5], v[238:241], v[226:229], v[6:9]
	v_mfma_f32_16x16x32_bf16 v[6:9], v[242:245], v[226:229], v[106:109]
	s_setprio 0
	v_mul_f32_e32 v61, 0xbfb8aa3b, v62
	v_exp_f32_e32 v61, v61
	s_ashr_i32 s0, s40, 1
	v_or_b32_e32 v60, s0, v126
	v_add_u32_e32 v0, s42, v125
	v_add_f32_e32 v61, 1.0, v61
	v_rcp_f32_e32 v61, v61
	v_mov_b64_e32 v[58:59], s[20:21]
	v_mad_i64_i32 v[94:95], s[0:1], v0, s4, v[58:59]
	v_mul_f32_e32 v61, v62, v61
	v_mul_f32_e32 v62, 0xbfb8aa3b, v63
	v_exp_f32_e32 v62, v62
	v_mul_f32_e32 v61, v166, v61
	s_and_b64 vcc, exec, s[34:35]
	v_add_f32_e32 v62, 1.0, v62
	v_rcp_f32_e32 v62, v62
	s_nop 0
	v_mul_f32_e32 v62, v63, v62
	v_mul_f32_e32 v63, 0xbfb8aa3b, v64
	v_exp_f32_e32 v63, v63
	v_mul_f32_e32 v62, v167, v62
	v_cvt_pk_bf16_f32 v62, v61, v62
	s_nop 1
	v_ashrrev_i32_e32 v61, 31, v60
	v_add_f32_e32 v63, 1.0, v63
	v_rcp_f32_e32 v63, v63
	v_lshlrev_b64 v[60:61], 1, v[60:61]
	v_mul_f32_e32 v63, v64, v63
	v_mul_f32_e32 v64, 0xbfb8aa3b, v65
	v_exp_f32_e32 v64, v64
	v_mul_f32_e32 v63, v168, v63
	v_add_f32_e32 v64, 1.0, v64
	v_rcp_f32_e32 v64, v64
	s_nop 0
	v_mul_f32_e32 v64, v65, v64
	v_mul_f32_e32 v64, v169, v64
	v_cvt_pk_bf16_f32 v63, v63, v64
	s_nop 1
	v_lshl_add_u64 v[64:65], v[94:95], 0, v[60:61]
	global_store_dwordx2 v[64:65], v[62:63], off
	v_mul_f32_e32 v62, 0xbfb8aa3b, v50
	v_exp_f32_e32 v62, v62
	s_nop 0
	v_add_f32_e32 v62, 1.0, v62
	v_rcp_f32_e32 v62, v62
	s_nop 0
	v_mul_f32_e32 v50, v50, v62
	v_mul_f32_e32 v50, v54, v50
	v_mul_f32_e32 v54, 0xbfb8aa3b, v51
	v_exp_f32_e32 v54, v54
	s_nop 0
	v_add_f32_e32 v54, 1.0, v54
	v_rcp_f32_e32 v54, v54
	s_nop 0
	v_mul_f32_e32 v51, v51, v54
	v_mul_f32_e32 v54, 0xbfb8aa3b, v52
	v_exp_f32_e32 v54, v54
	v_mul_f32_e32 v51, v55, v51
	v_cvt_pk_bf16_f32 v50, v50, v51
	s_nop 1
	v_add_f32_e32 v54, 1.0, v54
	v_rcp_f32_e32 v54, v54
	s_nop 0
	v_mul_f32_e32 v52, v52, v54
	v_mul_f32_e32 v54, 0xbfb8aa3b, v53
	v_exp_f32_e32 v54, v54
	v_mul_f32_e32 v52, v56, v52
	v_add_f32_e32 v54, 1.0, v54
	v_rcp_f32_e32 v54, v54
	s_nop 0
	v_mul_f32_e32 v53, v53, v54
	v_mul_f32_e32 v53, v57, v53
	v_cvt_pk_bf16_f32 v51, v52, v53
	s_nop 1
	v_mul_f32_e32 v52, 0xbfb8aa3b, v42
	v_exp_f32_e32 v52, v52
	global_store_dwordx2 v[64:65], v[50:51], off offset:32
	v_or_b32_e32 v50, 16, v0
	v_mad_i64_i32 v[50:51], s[0:1], v50, s4, v[58:59]
	v_add_f32_e32 v52, 1.0, v52
	v_rcp_f32_e32 v52, v52
	s_nop 0
	v_mul_f32_e32 v42, v42, v52
	v_mul_f32_e32 v42, v46, v42
	v_mul_f32_e32 v46, 0xbfb8aa3b, v43
	v_exp_f32_e32 v46, v46
	s_nop 0
	v_add_f32_e32 v46, 1.0, v46
	v_rcp_f32_e32 v46, v46
	s_nop 0
	v_mul_f32_e32 v43, v43, v46
	v_mul_f32_e32 v46, 0xbfb8aa3b, v44
	v_exp_f32_e32 v46, v46
	v_mul_f32_e32 v43, v47, v43
	v_cvt_pk_bf16_f32 v42, v42, v43
	s_nop 1
	v_add_f32_e32 v46, 1.0, v46
	v_rcp_f32_e32 v46, v46
	s_nop 0
	v_mul_f32_e32 v44, v44, v46
	v_mul_f32_e32 v46, 0xbfb8aa3b, v45
	v_exp_f32_e32 v46, v46
	v_mul_f32_e32 v44, v48, v44
	v_add_f32_e32 v46, 1.0, v46
	v_rcp_f32_e32 v46, v46
	s_nop 0
	v_mul_f32_e32 v45, v45, v46
	v_mul_f32_e32 v45, v49, v45
	v_cvt_pk_bf16_f32 v43, v44, v45
	s_nop 1
	v_lshl_add_u64 v[44:45], v[50:51], 0, v[60:61]
	global_store_dwordx2 v[44:45], v[42:43], off
	v_mul_f32_e32 v42, 0xbfb8aa3b, v34
	v_exp_f32_e32 v42, v42
	s_nop 0
	v_add_f32_e32 v42, 1.0, v42
	v_rcp_f32_e32 v42, v42
	s_nop 0
	v_mul_f32_e32 v34, v34, v42
	v_mul_f32_e32 v34, v38, v34
	v_mul_f32_e32 v38, 0xbfb8aa3b, v35
	v_exp_f32_e32 v38, v38
	s_nop 0
	v_add_f32_e32 v38, 1.0, v38
	v_rcp_f32_e32 v38, v38
	s_nop 0
	v_mul_f32_e32 v35, v35, v38
	v_mul_f32_e32 v38, 0xbfb8aa3b, v36
	v_exp_f32_e32 v38, v38
	v_mul_f32_e32 v35, v39, v35
	v_cvt_pk_bf16_f32 v34, v34, v35
	s_nop 1
	v_add_f32_e32 v38, 1.0, v38
	v_rcp_f32_e32 v38, v38
	s_nop 0
	v_mul_f32_e32 v36, v36, v38
	v_mul_f32_e32 v38, 0xbfb8aa3b, v37
	v_exp_f32_e32 v38, v38
	v_mul_f32_e32 v36, v40, v36
	v_add_f32_e32 v38, 1.0, v38
	v_rcp_f32_e32 v38, v38
	s_nop 0
	v_mul_f32_e32 v37, v37, v38
	v_mul_f32_e32 v37, v41, v37
	v_cvt_pk_bf16_f32 v35, v36, v37
	s_nop 1
	v_mul_f32_e32 v36, 0xbfb8aa3b, v26
	v_exp_f32_e32 v36, v36
	global_store_dwordx2 v[44:45], v[34:35], off offset:32
	v_or_b32_e32 v34, 32, v0
	v_mad_i64_i32 v[34:35], s[0:1], v34, s4, v[58:59]
	v_add_f32_e32 v36, 1.0, v36
	v_rcp_f32_e32 v36, v36
	v_or_b32_e32 v0, 48, v0
	v_mul_f32_e32 v26, v26, v36
	v_mul_f32_e32 v26, v30, v26
	v_mul_f32_e32 v30, 0xbfb8aa3b, v27
	v_exp_f32_e32 v30, v30
	s_nop 0
	v_add_f32_e32 v30, 1.0, v30
	v_rcp_f32_e32 v30, v30
	s_nop 0
	v_mul_f32_e32 v27, v27, v30
	v_mul_f32_e32 v30, 0xbfb8aa3b, v28
	v_exp_f32_e32 v30, v30
	v_mul_f32_e32 v27, v31, v27
	v_cvt_pk_bf16_f32 v26, v26, v27
	s_nop 1
	v_add_f32_e32 v30, 1.0, v30
	v_rcp_f32_e32 v30, v30
	s_nop 0
	v_mul_f32_e32 v28, v28, v30
	v_mul_f32_e32 v30, 0xbfb8aa3b, v29
	v_exp_f32_e32 v30, v30
	v_mul_f32_e32 v28, v32, v28
	v_add_f32_e32 v30, 1.0, v30
	v_rcp_f32_e32 v30, v30
	s_nop 0
	v_mul_f32_e32 v29, v29, v30
	v_mul_f32_e32 v29, v33, v29
	v_cvt_pk_bf16_f32 v27, v28, v29
	s_nop 1
	v_lshl_add_u64 v[28:29], v[34:35], 0, v[60:61]
	global_store_dwordx2 v[28:29], v[26:27], off
	v_mul_f32_e32 v26, 0xbfb8aa3b, v18
	v_exp_f32_e32 v26, v26
	s_nop 0
	v_add_f32_e32 v26, 1.0, v26
	v_rcp_f32_e32 v26, v26
	s_nop 0
	v_mul_f32_e32 v18, v18, v26
	v_mul_f32_e32 v18, v22, v18
	v_mul_f32_e32 v22, 0xbfb8aa3b, v19
	v_exp_f32_e32 v22, v22
	s_nop 0
	v_add_f32_e32 v22, 1.0, v22
	v_rcp_f32_e32 v22, v22
	s_nop 0
	v_mul_f32_e32 v19, v19, v22
	v_mul_f32_e32 v22, 0xbfb8aa3b, v20
	v_exp_f32_e32 v22, v22
	v_mul_f32_e32 v19, v23, v19
	v_cvt_pk_bf16_f32 v18, v18, v19
	s_nop 1
	v_add_f32_e32 v22, 1.0, v22
	v_rcp_f32_e32 v22, v22
	s_nop 0
	v_mul_f32_e32 v20, v20, v22
	v_mul_f32_e32 v22, 0xbfb8aa3b, v21
	v_exp_f32_e32 v22, v22
	v_mul_f32_e32 v20, v24, v20
	v_add_f32_e32 v22, 1.0, v22
	v_rcp_f32_e32 v22, v22
	s_nop 0
	v_mul_f32_e32 v21, v21, v22
	v_mul_f32_e32 v21, v25, v21
	v_cvt_pk_bf16_f32 v19, v20, v21
	s_nop 1
	global_store_dwordx2 v[28:29], v[18:19], off offset:32
	v_mad_i64_i32 v[18:19], s[0:1], v0, s4, v[58:59]
	v_mul_f32_e32 v0, 0xbfb8aa3b, v10
	v_exp_f32_e32 v0, v0
	s_mov_b32 s0, s19
	v_add_f32_e32 v0, 1.0, v0
	v_rcp_f32_e32 v0, v0
	s_nop 0
	v_mul_f32_e32 v0, v10, v0
	v_mul_f32_e32 v10, 0xbfb8aa3b, v11
	v_exp_f32_e32 v10, v10
	v_mul_f32_e32 v0, v14, v0
	v_add_f32_e32 v10, 1.0, v10
	v_rcp_f32_e32 v10, v10
	s_nop 0
	v_mul_f32_e32 v10, v11, v10
	v_mul_f32_e32 v10, v15, v10
	v_cvt_pk_bf16_f32 v10, v0, v10
	s_nop 1
	v_mul_f32_e32 v0, 0xbfb8aa3b, v2
	v_exp_f32_e32 v0, v0
	v_mul_f32_e32 v11, 0xbfb8aa3b, v12
	v_exp_f32_e32 v11, v11
	v_add_f32_e32 v0, 1.0, v0
	v_rcp_f32_e32 v0, v0
	v_add_f32_e32 v11, 1.0, v11
	v_rcp_f32_e32 v11, v11
	v_mul_f32_e32 v0, v2, v0
	v_mul_f32_e32 v2, 0xbfb8aa3b, v3
	v_exp_f32_e32 v2, v2
	v_mul_f32_e32 v11, v12, v11
	v_mul_f32_e32 v12, 0xbfb8aa3b, v13
	v_exp_f32_e32 v12, v12
	v_add_f32_e32 v2, 1.0, v2
	v_rcp_f32_e32 v2, v2
	v_mul_f32_e32 v11, v16, v11
	v_add_f32_e32 v12, 1.0, v12
	v_rcp_f32_e32 v12, v12
	v_mul_f32_e32 v2, v3, v2
	v_mul_f32_e32 v3, 0xbfb8aa3b, v4
	v_exp_f32_e32 v3, v3
	v_mul_f32_e32 v12, v13, v12
	v_mul_f32_e32 v12, v17, v12
	v_cvt_pk_bf16_f32 v11, v11, v12
	s_nop 1
	v_add_f32_e32 v3, 1.0, v3
	v_rcp_f32_e32 v3, v3
	v_lshl_add_u64 v[12:13], v[18:19], 0, v[60:61]
	v_mul_f32_e32 v2, v7, v2
	global_store_dwordx2 v[12:13], v[10:11], off
	v_mul_f32_e32 v3, v4, v3
	v_mul_f32_e32 v4, 0xbfb8aa3b, v5
	v_exp_f32_e32 v4, v4
	v_mul_f32_e32 v3, v8, v3
	v_mul_f32_e32 v0, v6, v0
	v_cvt_pk_bf16_f32 v2, v0, v2
	s_nop 1
	v_add_f32_e32 v4, 1.0, v4
	v_rcp_f32_e32 v4, v4
	s_nop 0
	v_mul_f32_e32 v4, v5, v4
	v_mul_f32_e32 v4, v9, v4
	v_cvt_pk_bf16_f32 v3, v3, v4
	s_nop 1
	global_store_dwordx2 v[12:13], v[2:3], off offset:32
	s_cbranch_vccnz .LBB0_1003

.LBB0_1000:
	s_and_b32 s0, s33, 0x2000
	s_xor_b32 s1, s0, 0x2000
	s_lshl_b32 s0, s0, 1
	v_add_u32_e32 v0, s0, v123
	v_add_u32_e32 v129, s0, v124
	v_add_u32_e32 v142, v0, v127
	v_add_u32_e32 v158, v129, v127
	ds_read_b128 v[130:133], v142
	ds_read_b128 v[134:137], v142 offset:2048
	ds_read_b128 v[138:141], v142 offset:4096
	ds_read_b128 v[142:145], v142 offset:6144
	ds_read_b128 v[146:149], v158 offset:32768
	ds_read_b128 v[150:153], v158 offset:34816
	ds_read_b128 v[154:157], v158 offset:36864
	ds_read_b128 v[158:161], v158 offset:38912
	v_lshl_add_u32 v250, s1, 1, v110
	v_lshl_add_u32 v255, v119, 1, v250
	v_add_u32_e32 v180, 0x8000, v255
	v_readfirstlane_b32 s1, v255
	v_lshl_add_u64 v[246:247], v[94:95], 0, s[46:47]
	s_mov_b32 m0, s1
	v_readfirstlane_b32 s1, v180
	v_lshl_add_u32 v255, v120, 1, v250
	v_lshl_add_u64 v[248:249], v[102:103], 0, s[46:47]
	global_load_lds_dwordx4 v[246:247], off
	s_mov_b32 m0, s1
	v_add_u32_e32 v180, 0x8000, v255
	v_readfirstlane_b32 s1, v255
	global_load_lds_dwordx4 v[248:249], off
	v_lshl_add_u64 v[246:247], v[96:97], 0, s[46:47]
	s_mov_b32 m0, s1
	v_readfirstlane_b32 s1, v180
	v_lshl_add_u32 v255, v121, 1, v250
	v_lshl_add_u64 v[248:249], v[104:105], 0, s[46:47]
	global_load_lds_dwordx4 v[246:247], off
	s_mov_b32 m0, s1
	v_add_u32_e32 v180, 0x8000, v255
	v_readfirstlane_b32 s1, v255
	global_load_lds_dwordx4 v[248:249], off
	v_lshl_add_u64 v[246:247], v[98:99], 0, s[46:47]
	s_mov_b32 m0, s1
	v_readfirstlane_b32 s1, v180
	v_lshl_add_u32 v250, v122, 1, v250
	v_lshl_add_u64 v[248:249], v[106:107], 0, s[46:47]
	global_load_lds_dwordx4 v[246:247], off
	s_mov_b32 m0, s1
	v_add_u32_e32 v255, 0x8000, v250
	v_readfirstlane_b32 s1, v250
	global_load_lds_dwordx4 v[248:249], off
	v_lshl_add_u64 v[246:247], v[100:101], 0, s[46:47]
	s_mov_b32 m0, s1
	v_readfirstlane_b32 s1, v255
	v_lshl_add_u64 v[248:249], v[108:109], 0, s[46:47]
	global_load_lds_dwordx4 v[246:247], off
	s_mov_b32 m0, s1
	global_load_lds_dwordx4 v[248:249], off
	v_add_u32_e32 v0, v0, v128
	ds_read_b128 v[214:217], v0
	ds_read_b128 v[218:221], v0 offset:2048
	ds_read_b128 v[222:225], v0 offset:4096
	ds_read_b128 v[226:229], v0 offset:6144
	v_add_u32_e32 v0, v129, v128
	ds_read_b128 v[230:233], v0 offset:32768
	ds_read_b128 v[234:237], v0 offset:34816
	ds_read_b128 v[238:241], v0 offset:36864
	s_setprio 1
	s_waitcnt lgkmcnt(7)
	ds_read_b128 v[242:245], v0 offset:38912
	v_mfma_f32_16x16x32_bf16 v[62:65], v[146:149], v[130:133], v[62:65]
	v_mfma_f32_16x16x32_bf16 v[58:61], v[150:153], v[130:133], v[58:61]
	v_mfma_f32_16x16x32_bf16 v[54:57], v[154:157], v[130:133], v[54:57]
	v_mfma_f32_16x16x32_bf16 v[50:53], v[158:161], v[130:133], v[50:53]
	v_mfma_f32_16x16x32_bf16 v[46:49], v[146:149], v[134:137], v[46:49]
	v_mfma_f32_16x16x32_bf16 v[42:45], v[150:153], v[134:137], v[42:45]
	v_mfma_f32_16x16x32_bf16 v[38:41], v[154:157], v[134:137], v[38:41]
	v_mfma_f32_16x16x32_bf16 v[34:37], v[158:161], v[134:137], v[34:37]
	v_mfma_f32_16x16x32_bf16 v[30:33], v[146:149], v[138:141], v[30:33]
	v_mfma_f32_16x16x32_bf16 v[26:29], v[150:153], v[138:141], v[26:29]
	v_mfma_f32_16x16x32_bf16 v[22:25], v[154:157], v[138:141], v[22:25]
	v_mfma_f32_16x16x32_bf16 v[18:21], v[158:161], v[138:141], v[18:21]
	v_mfma_f32_16x16x32_bf16 v[14:17], v[146:149], v[142:145], v[14:17]
	v_mfma_f32_16x16x32_bf16 v[10:13], v[150:153], v[142:145], v[10:13]
	v_mfma_f32_16x16x32_bf16 v[6:9], v[154:157], v[142:145], v[6:9]
	v_mfma_f32_16x16x32_bf16 v[2:5], v[158:161], v[142:145], v[2:5]
	s_waitcnt lgkmcnt(0)
	v_mfma_f32_16x16x32_bf16 v[62:65], v[230:233], v[214:217], v[62:65]
	v_mfma_f32_16x16x32_bf16 v[58:61], v[234:237], v[214:217], v[58:61]
	v_mfma_f32_16x16x32_bf16 v[54:57], v[238:241], v[214:217], v[54:57]
	v_mfma_f32_16x16x32_bf16 v[50:53], v[242:245], v[214:217], v[50:53]
	v_mfma_f32_16x16x32_bf16 v[46:49], v[230:233], v[218:221], v[46:49]
	v_mfma_f32_16x16x32_bf16 v[42:45], v[234:237], v[218:221], v[42:45]
	v_mfma_f32_16x16x32_bf16 v[38:41], v[238:241], v[218:221], v[38:41]
	v_mfma_f32_16x16x32_bf16 v[34:37], v[242:245], v[218:221], v[34:37]
	v_mfma_f32_16x16x32_bf16 v[30:33], v[230:233], v[222:225], v[30:33]
	v_mfma_f32_16x16x32_bf16 v[26:29], v[234:237], v[222:225], v[26:29]
	v_mfma_f32_16x16x32_bf16 v[22:25], v[238:241], v[222:225], v[22:25]
	v_mfma_f32_16x16x32_bf16 v[18:21], v[242:245], v[222:225], v[18:21]
	v_mfma_f32_16x16x32_bf16 v[14:17], v[230:233], v[226:229], v[14:17]
	v_mfma_f32_16x16x32_bf16 v[10:13], v[234:237], v[226:229], v[10:13]
	v_mfma_f32_16x16x32_bf16 v[6:9], v[238:241], v[226:229], v[6:9]
	v_mfma_f32_16x16x32_bf16 v[2:5], v[242:245], v[226:229], v[2:5]
	s_setprio 0
	s_addk_i32 s33, 0x2000
	s_waitcnt vmcnt(0)
	s_add_u32 s46, s46, 0x80
	s_addc_u32 s47, s47, 0
	s_cmpk_eq_i32 s46, 0x780
	s_waitcnt vmcnt(0)
	s_barrier
	s_cbranch_scc0 .LBB0_1000
	s_andn2_b64 vcc, exec, s[44:45]
	s_cbranch_vccnz .LBB0_996
	v_lshl_add_u64 v[94:95], v[66:67], 0, s[52:53]
	v_readfirstlane_b32 s0, v111
	v_lshl_add_u64 v[96:97], v[94:95], 0, v[86:87]
	v_lshl_add_u64 v[102:103], v[68:69], 0, s[56:57]
	s_mov_b32 m0, s0
	v_readfirstlane_b32 s0, v112
	v_lshl_add_u64 v[104:105], v[102:103], 0, v[92:93]
	v_lshl_add_u64 v[106:107], v[102:103], 0, v[90:91]
	v_lshl_add_u64 v[108:109], v[102:103], 0, v[88:89]
	v_lshl_add_u64 v[102:103], v[102:103], 0, v[86:87]
	global_load_lds_dwordx4 v[96:97], off
	s_mov_b32 m0, s0
	v_readfirstlane_b32 s0, v113
	v_lshl_add_u64 v[98:99], v[94:95], 0, v[88:89]
	global_load_lds_dwordx4 v[102:103], off
	s_mov_b32 m0, s0
	v_readfirstlane_b32 s0, v114
	global_load_lds_dwordx4 v[98:99], off
	s_mov_b32 m0, s0
	v_readfirstlane_b32 s0, v115
	v_lshl_add_u64 v[100:101], v[94:95], 0, v[90:91]
	global_load_lds_dwordx4 v[108:109], off
	s_mov_b32 m0, s0
	v_readfirstlane_b32 s0, v116
	global_load_lds_dwordx4 v[100:101], off
	s_mov_b32 m0, s0
	v_readfirstlane_b32 s0, v117
	v_lshl_add_u64 v[94:95], v[94:95], 0, v[92:93]
	global_load_lds_dwordx4 v[106:107], off
	s_mov_b32 m0, s0
	v_readfirstlane_b32 s0, v118
	global_load_lds_dwordx4 v[94:95], off
	s_mov_b32 m0, s0
	s_nop 0
	global_load_lds_dwordx4 v[104:105], off
	s_branch .LBB0_996

.LBB0_1054:
	v_add_u32_e32 v99, v125, v128
	ds_read_b128 v[66:69], v99 offset:16384
	ds_read_b128 v[100:103], v99 offset:18432
	ds_read_b128 v[104:107], v99 offset:20480
	ds_read_b128 v[108:111], v99 offset:22528
	v_add_u32_e32 v99, v126, v128
	ds_read_b128 v[130:133], v99 offset:49152
	ds_read_b128 v[134:137], v99 offset:51200
	ds_read_b128 v[138:141], v99 offset:53248
	ds_read_b128 v[142:145], v99 offset:55296
	v_add_u32_e32 v99, v125, v129
	ds_read_b128 v[214:217], v99 offset:16384
	ds_read_b128 v[218:221], v99 offset:18432
	ds_read_b128 v[222:225], v99 offset:20480
	ds_read_b128 v[226:229], v99 offset:22528
	v_add_u32_e32 v99, v126, v129
	ds_read_b128 v[230:233], v99 offset:49152
	ds_read_b128 v[234:237], v99 offset:51200
	ds_read_b128 v[238:241], v99 offset:53248
	s_setprio 1
	s_waitcnt lgkmcnt(7)
	ds_read_b128 v[242:245], v99 offset:55296
	v_mfma_f32_16x16x32_bf16 v[2:5], v[130:133], v[66:69], v[2:5]
	v_mfma_f32_16x16x32_bf16 v[6:9], v[134:137], v[66:69], v[6:9]
	v_mfma_f32_16x16x32_bf16 v[10:13], v[138:141], v[66:69], v[10:13]
	v_mfma_f32_16x16x32_bf16 v[14:17], v[142:145], v[66:69], v[14:17]
	v_mfma_f32_16x16x32_bf16 v[18:21], v[130:133], v[100:103], v[18:21]
	v_mfma_f32_16x16x32_bf16 v[22:25], v[134:137], v[100:103], v[22:25]
	v_mfma_f32_16x16x32_bf16 v[26:29], v[138:141], v[100:103], v[26:29]
	v_mfma_f32_16x16x32_bf16 v[30:33], v[142:145], v[100:103], v[30:33]
	v_mfma_f32_16x16x32_bf16 v[34:37], v[130:133], v[104:107], v[34:37]
	v_mfma_f32_16x16x32_bf16 v[38:41], v[134:137], v[104:107], v[38:41]
	v_mfma_f32_16x16x32_bf16 v[42:45], v[138:141], v[104:107], v[42:45]
	v_mfma_f32_16x16x32_bf16 v[46:49], v[142:145], v[104:107], v[46:49]
	v_mfma_f32_16x16x32_bf16 v[50:53], v[130:133], v[108:111], v[50:53]
	v_mfma_f32_16x16x32_bf16 v[54:57], v[134:137], v[108:111], v[54:57]
	v_mfma_f32_16x16x32_bf16 v[100:103], v[138:141], v[108:111], v[58:61]
	v_mfma_f32_16x16x32_bf16 v[104:107], v[142:145], v[108:111], v[62:65]
	s_waitcnt lgkmcnt(0)
	v_mfma_f32_16x16x32_bf16 v[146:149], v[230:233], v[214:217], v[2:5]
	v_mfma_f32_16x16x32_bf16 v[150:153], v[234:237], v[214:217], v[6:9]
	v_mfma_f32_16x16x32_bf16 v[154:157], v[238:241], v[214:217], v[10:13]
	v_mfma_f32_16x16x32_bf16 v[158:161], v[242:245], v[214:217], v[14:17]
	v_mfma_f32_16x16x32_bf16 v[162:165], v[230:233], v[218:221], v[18:21]
	v_mfma_f32_16x16x32_bf16 v[166:169], v[234:237], v[218:221], v[22:25]
	v_mfma_f32_16x16x32_bf16 v[176:179], v[238:241], v[218:221], v[26:29]
	v_mfma_f32_16x16x32_bf16 v[180:183], v[242:245], v[218:221], v[30:33]
	v_mfma_f32_16x16x32_bf16 v[184:187], v[230:233], v[222:225], v[34:37]
	v_mfma_f32_16x16x32_bf16 v[210:213], v[234:237], v[222:225], v[38:41]
	v_mfma_f32_16x16x32_bf16 v[58:61], v[238:241], v[222:225], v[42:45]
	v_mfma_f32_16x16x32_bf16 v[66:69], v[242:245], v[222:225], v[46:49]
	v_mfma_f32_16x16x32_bf16 v[62:65], v[230:233], v[226:229], v[50:53]
	v_mfma_f32_16x16x32_bf16 v[54:57], v[234:237], v[226:229], v[54:57]
	v_mfma_f32_16x16x32_bf16 v[46:49], v[238:241], v[226:229], v[100:103]
	v_mfma_f32_16x16x32_bf16 v[2:5], v[242:245], v[226:229], v[104:107]
	s_setprio 0
	s_min_i32 s0, s19, 0x4000
	s_ashr_i32 s0, s0, 11
	s_add_i32 s0, s0, s24
	s_mul_hi_i32 s1, s0, 0x6000
	s_mulk_i32 s0, 0x6000
	v_add_u32_e32 v8, s19, v127
	s_add_u32 s22, s94, s0
	v_ashrrev_i32_e32 v9, 31, v8
	s_addc_u32 s27, s95, s1
	s_lshl_b64 s[0:1], s[38:39], 2
	v_lshlrev_b64 v[8:9], 12, v[8:9]
	s_add_u32 s26, s22, s0
	v_lshl_add_u64 v[10:11], s[94:95], 0, v[8:9]
	v_lshl_add_u64 v[8:9], s[92:93], 0, v[8:9]
	s_addc_u32 s27, s27, s1
	v_lshl_add_u64 v[10:11], v[10:11], 0, s[0:1]
	v_lshl_add_u64 v[8:9], v[8:9], 0, s[0:1]
	v_readlane_b32 s0, v253, 38
	v_lshl_add_u64 v[6:7], s[26:27], 0, v[0:1]
	v_mov_b32_e32 v99, v1
	v_lshl_add_u64 v[10:11], v[10:11], 0, v[0:1]
	v_lshl_add_u64 v[8:9], v[8:9], 0, v[0:1]
	v_readlane_b32 s1, v253, 39
	v_lshl_add_u64 v[6:7], v[6:7], 0, v[98:99]
	s_mov_b64 s[26:27], 0x13585000
	v_cndmask_b32_e64 v9, v11, v9, s[0:1]
	v_cndmask_b32_e64 v8, v10, v8, s[0:1]
	s_mov_b32 s0, 0x13585000
	v_lshl_add_u64 v[18:19], v[6:7], 0, s[26:27]
	v_add_co_u32_e32 v6, vcc, s0, v6
	v_lshl_add_u64 v[102:103], v[10:11], 0, v[98:99]
	s_nop 0
	v_addc_co_u32_e32 v7, vcc, 0, v7, vcc
	s_mov_b32 s0, 0x10000
	v_add_co_u32_e32 v38, vcc, s0, v102
	s_mov_b32 s1, 0x20000
	s_nop 0
	v_addc_co_u32_e32 v39, vcc, 0, v103, vcc
	v_add_co_u32_e32 v138, vcc, s1, v102
	v_lshl_add_u64 v[100:101], v[8:9], 0, v[98:99]
	s_nop 0
	v_addc_co_u32_e32 v139, vcc, 0, v103, vcc
	global_load_dwordx4 v[104:107], v[6:7], off
	s_nop 0
	global_load_dwordx4 v[6:9], v[102:103], off
	global_load_dwordx4 v[108:111], v[18:19], off offset:64
	global_load_dwordx4 v[10:13], v[102:103], off offset:64
	global_load_dwordx4 v[130:133], v[18:19], off offset:128
	global_load_dwordx4 v[14:17], v[102:103], off offset:128
	global_load_dwordx4 v[26:29], v[18:19], off offset:192
	s_nop 0
	global_load_dwordx4 v[18:21], v[102:103], off offset:192
	global_load_dwordx4 v[50:53], v[138:139], off offset:64
	global_load_dwordx4 v[134:137], v[138:139], off offset:128
	s_mov_b32 s19, 0x30000
	global_load_dwordx4 v[34:37], v[38:39], off offset:128
	global_load_dwordx4 v[42:45], v[138:139], off
	global_load_dwordx4 v[22:25], v[38:39], off
	global_load_dwordx4 v[30:33], v[38:39], off offset:64
	s_mov_b32 s96, 0x10000
	global_load_dwordx4 v[38:41], v[38:39], off offset:192
	s_mov_b32 s24, 0x20000
	s_waitcnt vmcnt(0)
	v_pk_fma_f32 v[6:7], v[146:147], v[104:105], v[6:7]
	v_pk_fma_f32 v[8:9], v[148:149], v[106:107], v[8:9]
	v_pk_fma_f32 v[10:11], v[150:151], v[108:109], v[10:11]
	v_pk_fma_f32 v[12:13], v[152:153], v[110:111], v[12:13]
	v_pk_fma_f32 v[14:15], v[154:155], v[130:131], v[14:15]
	v_pk_fma_f32 v[58:59], v[58:59], v[130:131], v[134:135]
	v_pk_fma_f32 v[60:61], v[60:61], v[132:133], v[136:137]
	global_load_dwordx4 v[134:137], v[138:139], off offset:192
	v_add_co_u32_e32 v138, vcc, s19, v102
	v_pk_fma_f32 v[22:23], v[162:163], v[104:105], v[22:23]
	s_nop 0
	v_addc_co_u32_e32 v139, vcc, 0, v103, vcc
	v_pk_fma_f32 v[42:43], v[184:185], v[104:105], v[42:43]
	v_pk_fma_f32 v[16:17], v[156:157], v[132:133], v[16:17]
	v_pk_fma_f32 v[18:19], v[158:159], v[26:27], v[18:19]
	v_pk_fma_f32 v[20:21], v[160:161], v[28:29], v[20:21]
	v_pk_fma_f32 v[24:25], v[164:165], v[106:107], v[24:25]
	v_pk_fma_f32 v[30:31], v[166:167], v[108:109], v[30:31]
	v_pk_fma_f32 v[32:33], v[168:169], v[110:111], v[32:33]
	v_pk_fma_f32 v[34:35], v[176:177], v[130:131], v[34:35]
	v_pk_fma_f32 v[36:37], v[178:179], v[132:133], v[36:37]
	v_pk_fma_f32 v[44:45], v[186:187], v[106:107], v[44:45]
	v_pk_fma_f32 v[50:51], v[210:211], v[108:109], v[50:51]
	v_pk_fma_f32 v[52:53], v[212:213], v[110:111], v[52:53]
	s_waitcnt vmcnt(0)
	v_pk_fma_f32 v[66:67], v[66:67], v[26:27], v[134:135]
	v_pk_fma_f32 v[68:69], v[68:69], v[28:29], v[136:137]
	global_load_dwordx4 v[134:137], v[138:139], off
	v_pk_fma_f32 v[38:39], v[180:181], v[26:27], v[38:39]
	v_pk_fma_f32 v[40:41], v[182:183], v[28:29], v[40:41]
	s_waitcnt vmcnt(0)
	v_pk_fma_f32 v[62:63], v[62:63], v[104:105], v[134:135]
	global_load_dwordx4 v[102:105], v[138:139], off offset:64
	v_pk_fma_f32 v[64:65], v[64:65], v[106:107], v[136:137]
	s_waitcnt vmcnt(0)
	v_pk_fma_f32 v[54:55], v[54:55], v[108:109], v[102:103]
	v_pk_fma_f32 v[56:57], v[56:57], v[110:111], v[104:105]
	global_load_dwordx4 v[102:105], v[138:139], off offset:128
	s_waitcnt vmcnt(0)
	v_pk_fma_f32 v[46:47], v[46:47], v[130:131], v[102:103]
	v_pk_fma_f32 v[48:49], v[48:49], v[132:133], v[104:105]
	global_load_dwordx4 v[102:105], v[138:139], off offset:192
	s_nop 0
	global_store_dwordx4 v[100:101], v[6:9], off
	global_store_dwordx4 v[100:101], v[10:13], off offset:64
	global_store_dwordx4 v[100:101], v[14:17], off offset:128
	global_store_dwordx4 v[100:101], v[18:21], off offset:192
	v_add_co_u32_e32 v6, vcc, s0, v100
	s_mov_b32 s0, s3
	s_nop 0
	v_addc_co_u32_e32 v7, vcc, 0, v101, vcc
	global_store_dwordx4 v[6:7], v[22:25], off
	global_store_dwordx4 v[6:7], v[30:33], off offset:64
	global_store_dwordx4 v[6:7], v[34:37], off offset:128
	global_store_dwordx4 v[6:7], v[38:41], off offset:192
	v_add_co_u32_e32 v6, vcc, s1, v100
	s_waitcnt vmcnt(8)
	v_pk_fma_f32 v[2:3], v[2:3], v[26:27], v[102:103]
	v_addc_co_u32_e32 v7, vcc, 0, v101, vcc
	global_store_dwordx4 v[6:7], v[42:45], off
	global_store_dwordx4 v[6:7], v[50:53], off offset:64
	global_store_dwordx4 v[6:7], v[58:61], off offset:128
	global_store_dwordx4 v[6:7], v[66:69], off offset:192
	v_add_co_u32_e32 v6, vcc, 0x30000, v100
	v_pk_fma_f32 v[4:5], v[4:5], v[28:29], v[104:105]
	s_nop 0
	v_addc_co_u32_e32 v7, vcc, 0, v101, vcc
	s_and_b64 vcc, exec, s[34:35]
	global_store_dwordx4 v[6:7], v[62:65], off
	global_store_dwordx4 v[6:7], v[54:57], off offset:64
	global_store_dwordx4 v[6:7], v[46:49], off offset:128
	global_store_dwordx4 v[6:7], v[2:5], off offset:192
	s_cbranch_vccnz .LBB0_1061

.LBB0_1058:
	s_and_b32 s0, s22, 0x2000
	s_xor_b32 s1, s0, 0x2000
	s_lshl_b32 s0, s0, 1
	v_add_u32_e32 v99, s0, v125
	v_add_u32_e32 v162, s0, v126
	v_add_u32_e32 v142, v99, v128
	v_add_u32_e32 v158, v162, v128
	ds_read_b128 v[130:133], v142
	ds_read_b128 v[134:137], v142 offset:2048
	ds_read_b128 v[138:141], v142 offset:4096
	ds_read_b128 v[142:145], v142 offset:6144
	ds_read_b128 v[146:149], v158 offset:32768
	ds_read_b128 v[150:153], v158 offset:34816
	ds_read_b128 v[154:157], v158 offset:36864
	ds_read_b128 v[158:161], v158 offset:38912
	v_lshl_add_u32 v250, s1, 1, v112
	v_lshl_add_u32 v255, v121, 1, v250
	v_add_u32_e32 v170, 0x8000, v255
	v_readfirstlane_b32 s1, v255
	v_lshl_add_u64 v[246:247], v[66:67], 0, s[42:43]
	s_mov_b32 m0, s1
	v_readfirstlane_b32 s1, v170
	v_lshl_add_u32 v255, v122, 1, v250
	v_lshl_add_u64 v[248:249], v[104:105], 0, s[42:43]
	global_load_lds_dwordx4 v[246:247], off
	s_mov_b32 m0, s1
	v_add_u32_e32 v170, 0x8000, v255
	v_readfirstlane_b32 s1, v255
	global_load_lds_dwordx4 v[248:249], off
	v_lshl_add_u64 v[246:247], v[68:69], 0, s[42:43]
	s_mov_b32 m0, s1
	v_readfirstlane_b32 s1, v170
	v_lshl_add_u32 v255, v123, 1, v250
	v_lshl_add_u64 v[248:249], v[106:107], 0, s[42:43]
	global_load_lds_dwordx4 v[246:247], off
	s_mov_b32 m0, s1
	v_add_u32_e32 v170, 0x8000, v255
	v_readfirstlane_b32 s1, v255
	global_load_lds_dwordx4 v[248:249], off
	v_lshl_add_u64 v[246:247], v[100:101], 0, s[42:43]
	s_mov_b32 m0, s1
	v_readfirstlane_b32 s1, v170
	v_lshl_add_u32 v250, v124, 1, v250
	v_lshl_add_u64 v[248:249], v[108:109], 0, s[42:43]
	global_load_lds_dwordx4 v[246:247], off
	s_mov_b32 m0, s1
	v_add_u32_e32 v255, 0x8000, v250
	v_readfirstlane_b32 s1, v250
	global_load_lds_dwordx4 v[248:249], off
	v_lshl_add_u64 v[246:247], v[102:103], 0, s[42:43]
	s_mov_b32 m0, s1
	v_readfirstlane_b32 s1, v255
	v_lshl_add_u64 v[248:249], v[110:111], 0, s[42:43]
	global_load_lds_dwordx4 v[246:247], off
	s_mov_b32 m0, s1
	global_load_lds_dwordx4 v[248:249], off
	v_add_u32_e32 v99, v99, v129
	ds_read_b128 v[214:217], v99
	ds_read_b128 v[218:221], v99 offset:2048
	ds_read_b128 v[222:225], v99 offset:4096
	ds_read_b128 v[226:229], v99 offset:6144
	v_add_u32_e32 v99, v162, v129
	ds_read_b128 v[230:233], v99 offset:32768
	ds_read_b128 v[234:237], v99 offset:34816
	ds_read_b128 v[238:241], v99 offset:36864
	s_setprio 1
	s_waitcnt lgkmcnt(7)
	ds_read_b128 v[242:245], v99 offset:38912
	v_mfma_f32_16x16x32_bf16 v[2:5], v[146:149], v[130:133], v[2:5]
	v_mfma_f32_16x16x32_bf16 v[6:9], v[150:153], v[130:133], v[6:9]
	v_mfma_f32_16x16x32_bf16 v[10:13], v[154:157], v[130:133], v[10:13]
	v_mfma_f32_16x16x32_bf16 v[14:17], v[158:161], v[130:133], v[14:17]
	v_mfma_f32_16x16x32_bf16 v[18:21], v[146:149], v[134:137], v[18:21]
	v_mfma_f32_16x16x32_bf16 v[22:25], v[150:153], v[134:137], v[22:25]
	v_mfma_f32_16x16x32_bf16 v[26:29], v[154:157], v[134:137], v[26:29]
	v_mfma_f32_16x16x32_bf16 v[30:33], v[158:161], v[134:137], v[30:33]
	v_mfma_f32_16x16x32_bf16 v[34:37], v[146:149], v[138:141], v[34:37]
	v_mfma_f32_16x16x32_bf16 v[38:41], v[150:153], v[138:141], v[38:41]
	v_mfma_f32_16x16x32_bf16 v[42:45], v[154:157], v[138:141], v[42:45]
	v_mfma_f32_16x16x32_bf16 v[46:49], v[158:161], v[138:141], v[46:49]
	v_mfma_f32_16x16x32_bf16 v[50:53], v[146:149], v[142:145], v[50:53]
	v_mfma_f32_16x16x32_bf16 v[54:57], v[150:153], v[142:145], v[54:57]
	v_mfma_f32_16x16x32_bf16 v[58:61], v[154:157], v[142:145], v[58:61]
	v_mfma_f32_16x16x32_bf16 v[62:65], v[158:161], v[142:145], v[62:65]
	s_waitcnt lgkmcnt(0)
	v_mfma_f32_16x16x32_bf16 v[2:5], v[230:233], v[214:217], v[2:5]
	v_mfma_f32_16x16x32_bf16 v[6:9], v[234:237], v[214:217], v[6:9]
	v_mfma_f32_16x16x32_bf16 v[10:13], v[238:241], v[214:217], v[10:13]
	v_mfma_f32_16x16x32_bf16 v[14:17], v[242:245], v[214:217], v[14:17]
	v_mfma_f32_16x16x32_bf16 v[18:21], v[230:233], v[218:221], v[18:21]
	v_mfma_f32_16x16x32_bf16 v[22:25], v[234:237], v[218:221], v[22:25]
	v_mfma_f32_16x16x32_bf16 v[26:29], v[238:241], v[218:221], v[26:29]
	v_mfma_f32_16x16x32_bf16 v[30:33], v[242:245], v[218:221], v[30:33]
	v_mfma_f32_16x16x32_bf16 v[34:37], v[230:233], v[222:225], v[34:37]
	v_mfma_f32_16x16x32_bf16 v[38:41], v[234:237], v[222:225], v[38:41]
	v_mfma_f32_16x16x32_bf16 v[42:45], v[238:241], v[222:225], v[42:45]
	v_mfma_f32_16x16x32_bf16 v[46:49], v[242:245], v[222:225], v[46:49]
	v_mfma_f32_16x16x32_bf16 v[50:53], v[230:233], v[226:229], v[50:53]
	v_mfma_f32_16x16x32_bf16 v[54:57], v[234:237], v[226:229], v[54:57]
	v_mfma_f32_16x16x32_bf16 v[58:61], v[238:241], v[226:229], v[58:61]
	v_mfma_f32_16x16x32_bf16 v[62:65], v[242:245], v[226:229], v[62:65]
	s_setprio 0
	s_waitcnt vmcnt(0)
	s_add_u32 s42, s42, 0x80
	s_addc_u32 s43, s43, 0
	s_addk_i32 s22, 0x2000
	s_cmpk_eq_i32 s42, 0x1580
	s_waitcnt vmcnt(0)
	s_barrier
	s_cbranch_scc0 .LBB0_1058
	s_andn2_b64 vcc, exec, s[40:41]
	s_cbranch_vccnz .LBB0_1054
	v_lshl_add_u64 v[66:67], s[44:45], 1, v[78:79]
	v_readfirstlane_b32 s0, v113
	v_lshl_add_u64 v[68:69], v[66:67], 0, v[70:71]
	v_lshl_add_u64 v[104:105], s[46:47], 1, v[80:81]
	s_mov_b32 m0, s0
	v_readfirstlane_b32 s0, v114
	v_lshl_add_u64 v[106:107], v[104:105], 0, v[76:77]
	v_lshl_add_u64 v[108:109], v[104:105], 0, v[74:75]
	v_lshl_add_u64 v[110:111], v[104:105], 0, v[72:73]
	v_lshl_add_u64 v[104:105], v[104:105], 0, v[70:71]
	global_load_lds_dwordx4 v[68:69], off
	s_mov_b32 m0, s0
	v_readfirstlane_b32 s0, v115
	v_lshl_add_u64 v[100:101], v[66:67], 0, v[72:73]
	global_load_lds_dwordx4 v[104:105], off
	s_mov_b32 m0, s0
	v_readfirstlane_b32 s0, v116
	global_load_lds_dwordx4 v[100:101], off
	s_mov_b32 m0, s0
	v_readfirstlane_b32 s0, v117
	v_lshl_add_u64 v[102:103], v[66:67], 0, v[74:75]
	global_load_lds_dwordx4 v[110:111], off
	s_mov_b32 m0, s0
	v_readfirstlane_b32 s0, v118
	global_load_lds_dwordx4 v[102:103], off
	s_mov_b32 m0, s0
	v_readfirstlane_b32 s0, v119
	v_lshl_add_u64 v[66:67], v[66:67], 0, v[76:77]
	global_load_lds_dwordx4 v[108:109], off
	s_mov_b32 m0, s0
	v_readfirstlane_b32 s0, v120
	global_load_lds_dwordx4 v[66:67], off
	s_mov_b32 m0, s0
	s_nop 0
	global_load_lds_dwordx4 v[106:107], off
	s_branch .LBB0_1054

	.amdhsa_kernel _Z6k_mega6Params
		.amdhsa_group_segment_fixed_size 0
		.amdhsa_private_segment_fixed_size 0
		.amdhsa_kernarg_size 496
		.amdhsa_user_sgpr_count 2
		.amdhsa_user_sgpr_dispatch_ptr 0
		.amdhsa_user_sgpr_queue_ptr 0
		.amdhsa_user_sgpr_kernarg_segment_ptr 1
		.amdhsa_user_sgpr_dispatch_id 0
		.amdhsa_user_sgpr_kernarg_preload_length 0
		.amdhsa_user_sgpr_kernarg_preload_offset 0
		.amdhsa_user_sgpr_private_segment_size 0
		.amdhsa_uses_dynamic_stack 0
		.amdhsa_enable_private_segment 0
		.amdhsa_system_sgpr_workgroup_id_x 1
		.amdhsa_system_sgpr_workgroup_id_y 0
		.amdhsa_system_sgpr_workgroup_id_z 0
		.amdhsa_system_sgpr_workgroup_info 0
		.amdhsa_system_vgpr_workitem_id 2
		.amdhsa_next_free_vgpr 256
		.amdhsa_next_free_sgpr 98
		.amdhsa_accum_offset 256
		.amdhsa_reserve_vcc 1
		.amdhsa_float_round_mode_32 0
		.amdhsa_float_round_mode_16_64 0
		.amdhsa_float_denorm_mode_32 3
		.amdhsa_float_denorm_mode_16_64 3
		.amdhsa_dx10_clamp 1
		.amdhsa_ieee_mode 1
		.amdhsa_fp16_overflow 0
		.amdhsa_tg_split 0
		.amdhsa_exception_fp_ieee_invalid_op 0
		.amdhsa_exception_fp_denorm_src 0
		.amdhsa_exception_fp_ieee_div_zero 0
		.amdhsa_exception_fp_ieee_overflow 0
		.amdhsa_exception_fp_ieee_underflow 0
		.amdhsa_exception_fp_ieee_inexact 0
		.amdhsa_exception_int_div_zero 0
	.end_amdhsa_kernel

.Lfunc_end0:
	.size	_Z6k_mega6Params, .Lfunc_end0-_Z6k_mega6Params
	.set _Z6k_mega6Params.num_vgpr, 256
	.set _Z6k_mega6Params.num_agpr, 0
	.set _Z6k_mega6Params.numbered_sgpr, 98
	.set _Z6k_mega6Params.num_named_barrier, 0
	.set _Z6k_mega6Params.private_seg_size, 0
	.set _Z6k_mega6Params.uses_vcc, 1
	.set _Z6k_mega6Params.uses_flat_scratch, 0
	.set _Z6k_mega6Params.has_dyn_sized_stack, 0
	.set _Z6k_mega6Params.has_recursion, 0
	.set _Z6k_mega6Params.has_indirect_call, 0

amdhsa.kernels:
  - .agpr_count:     0
    .args:
      - .offset:         0
        .size:           240
        .value_kind:     by_value
      - .offset:         240
        .size:           4
        .value_kind:     hidden_block_count_x
      - .offset:         244
        .size:           4
        .value_kind:     hidden_block_count_y
      - .offset:         248
        .size:           4
        .value_kind:     hidden_block_count_z
      - .offset:         252
        .size:           2
        .value_kind:     hidden_group_size_x
      - .offset:         254
        .size:           2
        .value_kind:     hidden_group_size_y
      - .offset:         256
        .size:           2
        .value_kind:     hidden_group_size_z
      - .offset:         258
        .size:           2
        .value_kind:     hidden_remainder_x
      - .offset:         260
        .size:           2
        .value_kind:     hidden_remainder_y
      - .offset:         262
        .size:           2
        .value_kind:     hidden_remainder_z
      - .offset:         280
        .size:           8
        .value_kind:     hidden_global_offset_x
      - .offset:         288
        .size:           8
        .value_kind:     hidden_global_offset_y
      - .offset:         296
        .size:           8
        .value_kind:     hidden_global_offset_z
      - .offset:         304
        .size:           2
        .value_kind:     hidden_grid_dims
      - .offset:         328
        .size:           8
        .value_kind:     hidden_multigrid_sync_arg
      - .offset:         360
        .size:           4
        .value_kind:     hidden_dynamic_lds_size
    .group_segment_fixed_size: 0
    .kernarg_segment_align: 8
    .kernarg_segment_size: 496
    .language:       OpenCL C
    .language_version:
      - 2
      - 0
    .max_flat_workgroup_size: 256
    .name:           _Z6k_mega6Params
    .private_segment_fixed_size: 0
    .sgpr_count:     104
    .sgpr_spill_count: 249
    .symbol:         _Z6k_mega6Params.kd
    .uniform_work_group_size: 1
    .uses_dynamic_stack: false
    .vgpr_count:     256
    .vgpr_spill_count: 0
    .wavefront_size: 64
